# P2: q-tile loads issued before the gate/cumsum arithmetic (into v[186:217]); first q/k-loop pass enters behind them
# baseline (speedup 1.0000x reference)
.LBB0_269:
	s_ashr_i32 s46, s44, 2
	s_ashr_i32 s47, s46, 31
	s_and_b32 s45, s44, 3
	s_lshl_b64 s[48:49], s[46:47], 14
	v_lshl_or_b32 v114, s45, 7, v84
	v_lshl_add_u64 v[2:3], v[66:67], 0, s[48:49]
	v_add_co_u32_e32 v4, vcc, 0x2000, v2
	v_lshlrev_b32_e32 v64, 2, v114
	s_nop 0
	v_addc_co_u32_e32 v5, vcc, 0, v3, vcc
	v_lshl_add_u64 v[14:15], s[16:17], 0, v[64:65]
	s_barrier
	global_load_dwordx4 v[20:23], v[2:3], off
	global_load_dwordx4 v[24:27], v[4:5], off
	v_add_co_u32_e32 v4, vcc, 0x1000, v14
	global_load_dword v2, v64, s[16:17] offset:2048
	s_nop 0
	v_addc_co_u32_e32 v5, vcc, 0, v15, vcc
	v_add_co_u32_e32 v6, vcc, s61, v14
	s_lshl_b32 s0, s45, 8
	s_nop 0
	v_addc_co_u32_e32 v7, vcc, 0, v15, vcc
	v_add_co_u32_e32 v16, vcc, 0x3000, v14
	s_mov_b64 s[50:51], 0
	s_nop 0
	v_addc_co_u32_e32 v17, vcc, 0, v15, vcc
	v_add_co_u32_e32 v18, vcc, 0x4000, v14
	s_nop 1
	v_addc_co_u32_e32 v19, vcc, 0, v15, vcc
	global_load_dword v10, v[4:5], off
	global_load_dword v12, v[4:5], off offset:2048
	global_load_dword v8, v[6:7], off
	global_load_dword v11, v[6:7], off offset:2048
	s_nop 0
	global_load_dword v7, v[16:17], off
	global_load_dword v9, v[16:17], off offset:2048
	global_load_dword v3, v[18:19], off
	global_load_dword v4, v[18:19], off offset:2048
	v_add_co_u32_e32 v16, vcc, 0x5000, v14
	s_nop 1
	v_addc_co_u32_e32 v17, vcc, 0, v15, vcc
	global_load_dword v5, v[16:17], off
	global_load_dword v6, v[16:17], off offset:2048
	s_nop 0
	global_load_dword v17, v64, s[16:17]
	v_add_co_u32_e32 v28, vcc, 0x6000, v14
	global_load_dword v18, v64, s[18:19]
	s_nop 0
	v_addc_co_u32_e32 v29, vcc, 0, v15, vcc
	v_add_co_u32_e32 v30, vcc, 0x7000, v14
	s_nop 1
	v_addc_co_u32_e32 v31, vcc, 0, v15, vcc
	global_load_dword v16, v[28:29], off offset:2048
	global_load_dword v14, v[28:29], off
	global_load_dword v15, v[30:31], off offset:2048
	global_load_dword v13, v[30:31], off
	s_waitcnt vmcnt(18)
	ds_write_b128 v86, v[20:23]
	s_waitcnt vmcnt(17)
	ds_write_b128 v86, v[24:27] offset:8192
	s_waitcnt lgkmcnt(0)
	s_barrier
	ds_read_b128 v[20:23], v63
	ds_read_b128 v[24:27], v63 offset:16
	ds_read_b128 v[28:31], v63 offset:32
	ds_read_b128 v[32:35], v63 offset:48
	s_waitcnt vmcnt(16) lgkmcnt(3)
	v_mul_f32_e32 v19, v21, v2
	s_waitcnt vmcnt(14)
	v_mul_f32_e32 v21, v23, v12
	v_fmac_f32_e32 v21, v22, v10
	s_waitcnt vmcnt(12) lgkmcnt(2)
	v_mul_f32_e32 v23, v25, v11
	v_fmac_f32_e32 v23, v24, v8
	s_waitcnt vmcnt(10)
	v_mul_f32_e32 v25, v27, v9
	v_fmac_f32_e32 v25, v26, v7
	s_waitcnt vmcnt(8) lgkmcnt(1)
	v_mul_f32_e32 v27, v29, v4
	v_fmac_f32_e32 v27, v28, v3
	s_waitcnt vmcnt(6)
	v_mul_f32_e32 v29, v31, v6
	s_waitcnt vmcnt(5)
	v_fmac_f32_e32 v19, v20, v17
	v_add_f32_e32 v19, v19, v21
	v_fmac_f32_e32 v29, v30, v5
	v_add_f32_e32 v20, v23, v25
	s_waitcnt vmcnt(4)
	v_add_f32_e32 v19, v18, v19
	v_add_f32_e32 v21, v27, v29
	v_add_f32_e32 v19, v19, v20
	v_add_f32_e32 v19, v19, v21
	s_waitcnt vmcnt(3) lgkmcnt(0)
	v_mul_f32_e32 v20, v33, v16
	s_waitcnt vmcnt(2)
	v_fmac_f32_e32 v20, v32, v14
	s_waitcnt vmcnt(1)
	v_mul_f32_e32 v21, v35, v15
	s_waitcnt vmcnt(0)
	v_lshl_add_u32 v218, s46, 8, v88
	s_mov_b32 s100, 0x30000
	s_mov_b32 s101, 0
	v_mad_i64_i32 v[218:219], s[98:99], v218, s66, v[68:69]
	v_lshl_add_u64 v[218:219], v[218:219], 0, s[0:1]
	v_lshl_add_u64 v[218:219], v[218:219], 0, v[70:71]
	global_load_dwordx4 v[186:189], v[218:219], off
	v_lshl_add_u64 v[218:219], v[218:219], 0, s[100:101]
	global_load_dwordx4 v[190:193], v[218:219], off
	v_lshl_add_u64 v[218:219], v[218:219], 0, s[100:101]
	global_load_dwordx4 v[194:197], v[218:219], off
	v_lshl_add_u64 v[218:219], v[218:219], 0, s[100:101]
	global_load_dwordx4 v[198:201], v[218:219], off
	v_lshl_add_u64 v[218:219], v[218:219], 0, s[100:101]
	global_load_dwordx4 v[202:205], v[218:219], off
	v_lshl_add_u64 v[218:219], v[218:219], 0, s[100:101]
	global_load_dwordx4 v[206:209], v[218:219], off
	v_lshl_add_u64 v[218:219], v[218:219], 0, s[100:101]
	global_load_dwordx4 v[210:213], v[218:219], off
	v_lshl_add_u64 v[218:219], v[218:219], 0, s[100:101]
	global_load_dwordx4 v[214:217], v[218:219], off
	v_fmac_f32_e32 v21, v34, v13
	v_add_f32_e32 v20, v20, v21
	v_add_f32_e32 v19, v19, v20
	v_mul_f32_e64 v20, |v19|, s64
	v_exp_f32_e32 v24, v20
	ds_read_b128 v[20:23], v63 offset:64
	v_min_f32_e32 v19, 0, v19
	v_add_f32_e32 v24, 1.0, v24
	v_log_f32_e32 v28, v24
	ds_read_b128 v[24:27], v63 offset:80
	s_waitcnt lgkmcnt(1)
	v_mul_f32_e32 v21, v21, v2
	v_fmac_f32_e32 v21, v20, v17
	v_mul_f32_e32 v20, v23, v12
	v_fmac_f32_e32 v20, v22, v10
	v_add_f32_e32 v20, v21, v20
	s_waitcnt lgkmcnt(0)
	v_mul_f32_e32 v25, v25, v11
	v_add_f32_e32 v29, v18, v20
	v_fmac_f32_e32 v25, v24, v8
	v_mul_f32_e32 v24, v27, v9
	ds_read_b128 v[20:23], v63 offset:96
	v_fmac_f32_e32 v24, v26, v7
	v_add_f32_e32 v24, v25, v24
	v_add_f32_e32 v29, v29, v24
	ds_read_b128 v[24:27], v63 offset:112
	s_waitcnt lgkmcnt(1)
	v_mul_f32_e32 v21, v21, v4
	v_fmac_f32_e32 v21, v20, v3
	v_mul_f32_e32 v20, v23, v6
	v_fmac_f32_e32 v20, v22, v5
	v_add_f32_e32 v20, v21, v20
	s_waitcnt lgkmcnt(0)
	v_mul_f32_e32 v21, v25, v16
	v_mul_f32_e32 v22, v27, v15
	v_fmac_f32_e32 v21, v24, v14
	v_fmac_f32_e32 v22, v26, v13
	v_add_f32_e32 v20, v29, v20
	v_add_f32_e32 v21, v21, v22
	v_add_f32_e32 v24, v20, v21
	v_mul_f32_e64 v20, |v24|, s64
	v_exp_f32_e32 v20, v20
	v_fmac_f32_e32 v19, 0xbf317218, v28
	v_min_f32_e32 v28, 0, v24
	v_fma_f32 v19, v19, s65, 0
	v_add_f32_e32 v20, 1.0, v20
	v_log_f32_e32 v25, v20
	ds_read_b128 v[20:23], v63 offset:128
	v_fmac_f32_e32 v28, 0xbf317218, v25
	ds_read_b128 v[24:27], v63 offset:144
	s_waitcnt lgkmcnt(1)
	v_mul_f32_e32 v21, v21, v2
	v_fmac_f32_e32 v21, v20, v17
	v_mul_f32_e32 v20, v23, v12
	v_fmac_f32_e32 v20, v22, v10
	v_add_f32_e32 v20, v21, v20
	s_waitcnt lgkmcnt(0)
	v_mul_f32_e32 v25, v25, v11
	v_add_f32_e32 v29, v18, v20
	v_fmac_f32_e32 v25, v24, v8
	v_mul_f32_e32 v24, v27, v9
	ds_read_b128 v[20:23], v63 offset:160
	v_fmac_f32_e32 v24, v26, v7
	v_add_f32_e32 v24, v25, v24
	v_add_f32_e32 v29, v29, v24
	ds_read_b128 v[24:27], v63 offset:176
	s_waitcnt lgkmcnt(1)
	v_mul_f32_e32 v21, v21, v4
	v_fmac_f32_e32 v21, v20, v3
	v_mul_f32_e32 v20, v23, v6
	v_fmac_f32_e32 v20, v22, v5
	v_add_f32_e32 v20, v21, v20
	s_waitcnt lgkmcnt(0)
	v_mul_f32_e32 v21, v25, v16
	v_mul_f32_e32 v22, v27, v15
	v_fmac_f32_e32 v21, v24, v14
	v_fmac_f32_e32 v22, v26, v13
	v_add_f32_e32 v20, v29, v20
	v_add_f32_e32 v21, v21, v22
	v_add_f32_e32 v21, v20, v21
	v_mul_f32_e64 v20, |v21|, s64
	v_exp_f32_e32 v26, v20
	ds_read_b128 v[22:25], v63 offset:192
	v_fmamk_f32 v20, v28, 0x3d800000, v19
	v_min_f32_e32 v21, 0, v21
	v_add_f32_e32 v26, 1.0, v26
	v_log_f32_e32 v30, v26
	ds_read_b128 v[26:29], v63 offset:208
	s_waitcnt lgkmcnt(1)
	v_mul_f32_e32 v23, v23, v2
	v_fmac_f32_e32 v23, v22, v17
	v_mul_f32_e32 v22, v25, v12
	v_fmac_f32_e32 v22, v24, v10
	v_add_f32_e32 v22, v23, v22
	s_waitcnt lgkmcnt(0)
	v_mul_f32_e32 v27, v27, v11
	v_add_f32_e32 v31, v18, v22
	v_fmac_f32_e32 v27, v26, v8
	v_mul_f32_e32 v26, v29, v9
	ds_read_b128 v[22:25], v63 offset:224
	v_fmac_f32_e32 v26, v28, v7
	v_add_f32_e32 v26, v27, v26
	v_add_f32_e32 v31, v31, v26
	ds_read_b128 v[26:29], v63 offset:240
	s_waitcnt lgkmcnt(1)
	v_mul_f32_e32 v23, v23, v4
	v_fmac_f32_e32 v23, v22, v3
	v_mul_f32_e32 v22, v25, v6
	v_fmac_f32_e32 v22, v24, v5
	v_add_f32_e32 v22, v23, v22
	s_waitcnt lgkmcnt(0)
	v_mul_f32_e32 v23, v27, v16
	v_mul_f32_e32 v24, v29, v15
	v_fmac_f32_e32 v23, v26, v14
	v_fmac_f32_e32 v24, v28, v13
	v_add_f32_e32 v22, v31, v22
	v_add_f32_e32 v23, v23, v24
	v_add_f32_e32 v31, v22, v23
	v_mul_f32_e64 v22, |v31|, s64
	v_exp_f32_e32 v26, v22
	ds_read_b128 v[22:25], v63 offset:256
	v_fmac_f32_e32 v21, 0xbf317218, v30
	v_min_f32_e32 v31, 0, v31
	v_add_f32_e32 v26, 1.0, v26
	v_log_f32_e32 v30, v26
	ds_read_b128 v[26:29], v63 offset:272
	s_waitcnt lgkmcnt(1)
	v_mul_f32_e32 v23, v23, v2
	v_fmac_f32_e32 v23, v22, v17
	v_mul_f32_e32 v22, v25, v12
	v_fmac_f32_e32 v22, v24, v10
	v_add_f32_e32 v22, v23, v22
	s_waitcnt lgkmcnt(0)
	v_mul_f32_e32 v27, v27, v11
	v_add_f32_e32 v32, v18, v22
	v_fmac_f32_e32 v27, v26, v8
	v_mul_f32_e32 v26, v29, v9
	ds_read_b128 v[22:25], v63 offset:288
	v_fmac_f32_e32 v26, v28, v7
	v_add_f32_e32 v26, v27, v26
	v_add_f32_e32 v32, v32, v26
	ds_read_b128 v[26:29], v63 offset:304
	s_waitcnt lgkmcnt(1)
	v_mul_f32_e32 v23, v23, v4
	v_fmac_f32_e32 v23, v22, v3
	v_mul_f32_e32 v22, v25, v6
	v_fmac_f32_e32 v22, v24, v5
	v_add_f32_e32 v22, v23, v22
	s_waitcnt lgkmcnt(0)
	v_mul_f32_e32 v23, v27, v16
	v_mul_f32_e32 v24, v29, v15
	v_fmac_f32_e32 v23, v26, v14
	v_fmac_f32_e32 v24, v28, v13
	v_add_f32_e32 v22, v32, v22
	v_add_f32_e32 v23, v23, v24
	v_add_f32_e32 v32, v22, v23
	v_mul_f32_e64 v22, |v32|, s64
	v_exp_f32_e32 v26, v22
	ds_read_b128 v[22:25], v63 offset:320
	v_fmac_f32_e32 v31, 0xbf317218, v30
	v_fmamk_f32 v21, v21, 0x3d800000, v20
	v_add_f32_e32 v26, 1.0, v26
	v_log_f32_e32 v30, v26
	ds_read_b128 v[26:29], v63 offset:336
	s_waitcnt lgkmcnt(1)
	v_mul_f32_e32 v23, v23, v2
	v_fmac_f32_e32 v23, v22, v17
	v_mul_f32_e32 v22, v25, v12
	v_fmac_f32_e32 v22, v24, v10
	v_add_f32_e32 v22, v23, v22
	s_waitcnt lgkmcnt(0)
	v_mul_f32_e32 v27, v27, v11
	v_add_f32_e32 v33, v18, v22
	v_fmac_f32_e32 v27, v26, v8
	v_mul_f32_e32 v26, v29, v9
	ds_read_b128 v[22:25], v63 offset:352
	v_fmac_f32_e32 v26, v28, v7
	v_add_f32_e32 v26, v27, v26
	v_add_f32_e32 v33, v33, v26
	ds_read_b128 v[26:29], v63 offset:368
	s_waitcnt lgkmcnt(1)
	v_mul_f32_e32 v23, v23, v4
	v_fmac_f32_e32 v23, v22, v3
	v_mul_f32_e32 v22, v25, v6
	v_fmac_f32_e32 v22, v24, v5
	v_add_f32_e32 v22, v23, v22
	s_waitcnt lgkmcnt(0)
	v_mul_f32_e32 v23, v27, v16
	v_mul_f32_e32 v24, v29, v15
	v_fmac_f32_e32 v23, v26, v14
	v_fmac_f32_e32 v24, v28, v13
	v_add_f32_e32 v22, v33, v22
	v_add_f32_e32 v23, v23, v24
	v_add_f32_e32 v28, v22, v23
	v_mul_f32_e64 v22, |v28|, s64
	v_exp_f32_e32 v23, v22
	v_min_f32_e32 v29, 0, v32
	v_fmac_f32_e32 v29, 0xbf317218, v30
	ds_read_b128 v[24:27], v63 offset:384
	v_add_f32_e32 v23, 1.0, v23
	v_log_f32_e32 v30, v23
	v_fmamk_f32 v22, v31, 0x3d800000, v21
	v_min_f32_e32 v32, 0, v28
	v_fmamk_f32 v23, v29, 0x3d800000, v22
	v_fmac_f32_e32 v32, 0xbf317218, v30
	ds_read_b128 v[28:31], v63 offset:400
	s_waitcnt lgkmcnt(1)
	v_mul_f32_e32 v25, v25, v2
	v_fmac_f32_e32 v25, v24, v17
	v_mul_f32_e32 v24, v27, v12
	v_fmac_f32_e32 v24, v26, v10
	v_add_f32_e32 v24, v25, v24
	s_waitcnt lgkmcnt(0)
	v_mul_f32_e32 v29, v29, v11
	v_add_f32_e32 v33, v18, v24
	v_fmac_f32_e32 v29, v28, v8
	v_mul_f32_e32 v28, v31, v9
	ds_read_b128 v[24:27], v63 offset:416
	v_fmac_f32_e32 v28, v30, v7
	v_add_f32_e32 v28, v29, v28
	v_add_f32_e32 v33, v33, v28
	ds_read_b128 v[28:31], v63 offset:432
	s_waitcnt lgkmcnt(1)
	v_mul_f32_e32 v25, v25, v4
	v_fmac_f32_e32 v25, v24, v3
	v_mul_f32_e32 v24, v27, v6
	v_fmac_f32_e32 v24, v26, v5
	v_add_f32_e32 v24, v25, v24
	s_waitcnt lgkmcnt(0)
	v_mul_f32_e32 v25, v29, v16
	v_mul_f32_e32 v26, v31, v15
	v_fmac_f32_e32 v25, v28, v14
	v_fmac_f32_e32 v26, v30, v13
	v_add_f32_e32 v24, v33, v24
	v_add_f32_e32 v25, v25, v26
	v_add_f32_e32 v25, v24, v25
	v_mul_f32_e64 v24, |v25|, s64
	v_exp_f32_e32 v30, v24
	ds_read_b128 v[26:29], v63 offset:448
	v_fmamk_f32 v24, v32, 0x3d800000, v23
	v_min_f32_e32 v25, 0, v25
	v_add_f32_e32 v30, 1.0, v30
	v_log_f32_e32 v34, v30
	ds_read_b128 v[30:33], v63 offset:464
	s_waitcnt lgkmcnt(1)
	v_mul_f32_e32 v27, v27, v2
	v_fmac_f32_e32 v27, v26, v17
	v_mul_f32_e32 v26, v29, v12
	v_fmac_f32_e32 v26, v28, v10
	v_add_f32_e32 v26, v27, v26
	s_waitcnt lgkmcnt(0)
	v_mul_f32_e32 v31, v31, v11
	v_add_f32_e32 v35, v18, v26
	v_fmac_f32_e32 v31, v30, v8
	v_mul_f32_e32 v30, v33, v9
	ds_read_b128 v[26:29], v63 offset:480
	v_fmac_f32_e32 v30, v32, v7
	v_add_f32_e32 v30, v31, v30
	v_add_f32_e32 v35, v35, v30
	ds_read_b128 v[30:33], v63 offset:496
	s_waitcnt lgkmcnt(1)
	v_mul_f32_e32 v27, v27, v4
	v_fmac_f32_e32 v27, v26, v3
	v_mul_f32_e32 v26, v29, v6
	v_fmac_f32_e32 v26, v28, v5
	v_add_f32_e32 v26, v27, v26
	s_waitcnt lgkmcnt(0)
	v_mul_f32_e32 v27, v31, v16
	v_mul_f32_e32 v28, v33, v15
	v_fmac_f32_e32 v27, v30, v14
	v_fmac_f32_e32 v28, v32, v13
	v_add_f32_e32 v26, v35, v26
	v_add_f32_e32 v27, v27, v28
	v_add_f32_e32 v35, v26, v27
	v_mul_f32_e64 v26, |v35|, s64
	v_exp_f32_e32 v30, v26
	ds_read_b128 v[26:29], v63 offset:512
	v_fmac_f32_e32 v25, 0xbf317218, v34
	v_min_f32_e32 v35, 0, v35
	v_add_f32_e32 v30, 1.0, v30
	v_log_f32_e32 v34, v30
	ds_read_b128 v[30:33], v63 offset:528
	s_waitcnt lgkmcnt(1)
	v_mul_f32_e32 v27, v27, v2
	v_fmac_f32_e32 v27, v26, v17
	v_mul_f32_e32 v26, v29, v12
	v_fmac_f32_e32 v26, v28, v10
	v_add_f32_e32 v26, v27, v26
	s_waitcnt lgkmcnt(0)
	v_mul_f32_e32 v31, v31, v11
	v_add_f32_e32 v36, v18, v26
	v_fmac_f32_e32 v31, v30, v8
	v_mul_f32_e32 v30, v33, v9
	ds_read_b128 v[26:29], v63 offset:544
	v_fmac_f32_e32 v30, v32, v7
	v_add_f32_e32 v30, v31, v30
	v_add_f32_e32 v36, v36, v30
	ds_read_b128 v[30:33], v63 offset:560
	s_waitcnt lgkmcnt(1)
	v_mul_f32_e32 v27, v27, v4
	v_fmac_f32_e32 v27, v26, v3
	v_mul_f32_e32 v26, v29, v6
	v_fmac_f32_e32 v26, v28, v5
	v_add_f32_e32 v26, v27, v26
	s_waitcnt lgkmcnt(0)
	v_mul_f32_e32 v27, v31, v16
	v_mul_f32_e32 v28, v33, v15
	v_fmac_f32_e32 v27, v30, v14
	v_fmac_f32_e32 v28, v32, v13
	v_add_f32_e32 v26, v36, v26
	v_add_f32_e32 v27, v27, v28
	v_add_f32_e32 v36, v26, v27
	v_mul_f32_e64 v26, |v36|, s64
	v_exp_f32_e32 v30, v26
	ds_read_b128 v[26:29], v63 offset:576
	v_fmac_f32_e32 v35, 0xbf317218, v34
	v_fmamk_f32 v25, v25, 0x3d800000, v24
	v_add_f32_e32 v30, 1.0, v30
	v_log_f32_e32 v34, v30
	ds_read_b128 v[30:33], v63 offset:592
	s_waitcnt lgkmcnt(1)
	v_mul_f32_e32 v27, v27, v2
	v_fmac_f32_e32 v27, v26, v17
	v_mul_f32_e32 v26, v29, v12
	v_fmac_f32_e32 v26, v28, v10
	v_add_f32_e32 v26, v27, v26
	s_waitcnt lgkmcnt(0)
	v_mul_f32_e32 v31, v31, v11
	v_add_f32_e32 v37, v18, v26
	v_fmac_f32_e32 v31, v30, v8
	v_mul_f32_e32 v30, v33, v9
	ds_read_b128 v[26:29], v63 offset:608
	v_fmac_f32_e32 v30, v32, v7
	v_add_f32_e32 v30, v31, v30
	v_add_f32_e32 v37, v37, v30
	ds_read_b128 v[30:33], v63 offset:624
	s_waitcnt lgkmcnt(1)
	v_mul_f32_e32 v27, v27, v4
	v_fmac_f32_e32 v27, v26, v3
	v_mul_f32_e32 v26, v29, v6
	v_fmac_f32_e32 v26, v28, v5
	v_add_f32_e32 v26, v27, v26
	s_waitcnt lgkmcnt(0)
	v_mul_f32_e32 v27, v31, v16
	v_mul_f32_e32 v28, v33, v15
	v_fmac_f32_e32 v27, v30, v14
	v_fmac_f32_e32 v28, v32, v13
	v_add_f32_e32 v26, v37, v26
	v_add_f32_e32 v27, v27, v28
	v_add_f32_e32 v32, v26, v27
	v_mul_f32_e64 v26, |v32|, s64
	v_exp_f32_e32 v27, v26
	v_min_f32_e32 v33, 0, v36
	v_fmac_f32_e32 v33, 0xbf317218, v34
	ds_read_b128 v[28:31], v63 offset:640
	v_add_f32_e32 v27, 1.0, v27
	v_log_f32_e32 v34, v27
	v_fmamk_f32 v26, v35, 0x3d800000, v25
	v_min_f32_e32 v36, 0, v32
	v_fmamk_f32 v27, v33, 0x3d800000, v26
	v_fmac_f32_e32 v36, 0xbf317218, v34
	ds_read_b128 v[32:35], v63 offset:656
	s_waitcnt lgkmcnt(1)
	v_mul_f32_e32 v29, v29, v2
	v_fmac_f32_e32 v29, v28, v17
	v_mul_f32_e32 v28, v31, v12
	v_fmac_f32_e32 v28, v30, v10
	v_add_f32_e32 v28, v29, v28
	s_waitcnt lgkmcnt(0)
	v_mul_f32_e32 v33, v33, v11
	v_add_f32_e32 v37, v18, v28
	v_fmac_f32_e32 v33, v32, v8
	v_mul_f32_e32 v32, v35, v9
	ds_read_b128 v[28:31], v63 offset:672
	v_fmac_f32_e32 v32, v34, v7
	v_add_f32_e32 v32, v33, v32
	v_add_f32_e32 v37, v37, v32
	ds_read_b128 v[32:35], v63 offset:688
	s_waitcnt lgkmcnt(1)
	v_mul_f32_e32 v29, v29, v4
	v_fmac_f32_e32 v29, v28, v3
	v_mul_f32_e32 v28, v31, v6
	v_fmac_f32_e32 v28, v30, v5
	v_add_f32_e32 v28, v29, v28
	s_waitcnt lgkmcnt(0)
	v_mul_f32_e32 v29, v33, v16
	v_mul_f32_e32 v30, v35, v15
	v_fmac_f32_e32 v29, v32, v14
	v_fmac_f32_e32 v30, v34, v13
	v_add_f32_e32 v28, v37, v28
	v_add_f32_e32 v29, v29, v30
	v_add_f32_e32 v29, v28, v29
	v_mul_f32_e64 v28, |v29|, s64
	v_exp_f32_e32 v34, v28
	ds_read_b128 v[30:33], v63 offset:704
	v_fmamk_f32 v28, v36, 0x3d800000, v27
	v_min_f32_e32 v29, 0, v29
	v_add_f32_e32 v34, 1.0, v34
	v_log_f32_e32 v38, v34
	ds_read_b128 v[34:37], v63 offset:720
	s_waitcnt lgkmcnt(1)
	v_mul_f32_e32 v31, v31, v2
	v_fmac_f32_e32 v31, v30, v17
	v_mul_f32_e32 v30, v33, v12
	v_fmac_f32_e32 v30, v32, v10
	v_add_f32_e32 v30, v31, v30
	s_waitcnt lgkmcnt(0)
	v_mul_f32_e32 v35, v35, v11
	v_add_f32_e32 v39, v18, v30
	v_fmac_f32_e32 v35, v34, v8
	v_mul_f32_e32 v34, v37, v9
	ds_read_b128 v[30:33], v63 offset:736
	v_fmac_f32_e32 v34, v36, v7
	v_add_f32_e32 v34, v35, v34
	v_add_f32_e32 v39, v39, v34
	ds_read_b128 v[34:37], v63 offset:752
	s_waitcnt lgkmcnt(1)
	v_mul_f32_e32 v31, v31, v4
	v_fmac_f32_e32 v31, v30, v3
	v_mul_f32_e32 v30, v33, v6
	v_fmac_f32_e32 v30, v32, v5
	v_add_f32_e32 v30, v31, v30
	s_waitcnt lgkmcnt(0)
	v_mul_f32_e32 v31, v35, v16
	v_mul_f32_e32 v32, v37, v15
	v_fmac_f32_e32 v31, v34, v14
	v_fmac_f32_e32 v32, v36, v13
	v_add_f32_e32 v30, v39, v30
	v_add_f32_e32 v31, v31, v32
	v_add_f32_e32 v39, v30, v31
	v_mul_f32_e64 v30, |v39|, s64
	v_exp_f32_e32 v34, v30
	ds_read_b128 v[30:33], v63 offset:768
	v_fmac_f32_e32 v29, 0xbf317218, v38
	v_min_f32_e32 v39, 0, v39
	v_add_f32_e32 v34, 1.0, v34
	v_log_f32_e32 v38, v34
	ds_read_b128 v[34:37], v63 offset:784
	s_waitcnt lgkmcnt(1)
	v_mul_f32_e32 v31, v31, v2
	v_fmac_f32_e32 v31, v30, v17
	v_mul_f32_e32 v30, v33, v12
	v_fmac_f32_e32 v30, v32, v10
	v_add_f32_e32 v30, v31, v30
	s_waitcnt lgkmcnt(0)
	v_mul_f32_e32 v35, v35, v11
	v_add_f32_e32 v40, v18, v30
	v_fmac_f32_e32 v35, v34, v8
	v_mul_f32_e32 v34, v37, v9
	ds_read_b128 v[30:33], v63 offset:800
	v_fmac_f32_e32 v34, v36, v7
	v_add_f32_e32 v34, v35, v34
	v_add_f32_e32 v40, v40, v34
	ds_read_b128 v[34:37], v63 offset:816
	s_waitcnt lgkmcnt(1)
	v_mul_f32_e32 v31, v31, v4
	v_fmac_f32_e32 v31, v30, v3
	v_mul_f32_e32 v30, v33, v6
	v_fmac_f32_e32 v30, v32, v5
	v_add_f32_e32 v30, v31, v30
	s_waitcnt lgkmcnt(0)
	v_mul_f32_e32 v31, v35, v16
	v_mul_f32_e32 v32, v37, v15
	v_fmac_f32_e32 v31, v34, v14
	v_fmac_f32_e32 v32, v36, v13
	v_add_f32_e32 v30, v40, v30
	v_add_f32_e32 v31, v31, v32
	v_add_f32_e32 v40, v30, v31
	v_mul_f32_e64 v30, |v40|, s64
	v_exp_f32_e32 v34, v30
	ds_read_b128 v[30:33], v63 offset:832
	v_fmac_f32_e32 v39, 0xbf317218, v38
	v_fmamk_f32 v29, v29, 0x3d800000, v28
	v_add_f32_e32 v34, 1.0, v34
	v_log_f32_e32 v38, v34
	ds_read_b128 v[34:37], v63 offset:848
	s_waitcnt lgkmcnt(1)
	v_mul_f32_e32 v31, v31, v2
	v_fmac_f32_e32 v31, v30, v17
	v_mul_f32_e32 v30, v33, v12
	v_fmac_f32_e32 v30, v32, v10
	v_add_f32_e32 v30, v31, v30
	s_waitcnt lgkmcnt(0)
	v_mul_f32_e32 v35, v35, v11
	v_add_f32_e32 v41, v18, v30
	v_fmac_f32_e32 v35, v34, v8
	v_mul_f32_e32 v34, v37, v9
	ds_read_b128 v[30:33], v63 offset:864
	v_fmac_f32_e32 v34, v36, v7
	v_add_f32_e32 v34, v35, v34
	v_add_f32_e32 v41, v41, v34
	ds_read_b128 v[34:37], v63 offset:880
	s_waitcnt lgkmcnt(1)
	v_mul_f32_e32 v31, v31, v4
	v_fmac_f32_e32 v31, v30, v3
	v_mul_f32_e32 v30, v33, v6
	v_fmac_f32_e32 v30, v32, v5
	v_add_f32_e32 v30, v31, v30
	s_waitcnt lgkmcnt(0)
	v_mul_f32_e32 v31, v35, v16
	v_mul_f32_e32 v32, v37, v15
	v_fmac_f32_e32 v31, v34, v14
	v_fmac_f32_e32 v32, v36, v13
	v_add_f32_e32 v30, v41, v30
	v_add_f32_e32 v31, v31, v32
	v_add_f32_e32 v36, v30, v31
	v_mul_f32_e64 v30, |v36|, s64
	v_exp_f32_e32 v31, v30
	v_min_f32_e32 v37, 0, v40
	v_fmac_f32_e32 v37, 0xbf317218, v38
	ds_read_b128 v[32:35], v63 offset:896
	v_add_f32_e32 v31, 1.0, v31
	v_log_f32_e32 v38, v31
	v_fmamk_f32 v30, v39, 0x3d800000, v29
	v_min_f32_e32 v40, 0, v36
	v_fmamk_f32 v31, v37, 0x3d800000, v30
	v_fmac_f32_e32 v40, 0xbf317218, v38
	ds_read_b128 v[36:39], v63 offset:912
	s_waitcnt lgkmcnt(1)
	v_mul_f32_e32 v33, v33, v2
	v_fmac_f32_e32 v33, v32, v17
	v_mul_f32_e32 v32, v35, v12
	v_fmac_f32_e32 v32, v34, v10
	v_add_f32_e32 v32, v33, v32
	s_waitcnt lgkmcnt(0)
	v_mul_f32_e32 v37, v37, v11
	v_add_f32_e32 v41, v18, v32
	v_fmac_f32_e32 v37, v36, v8
	v_mul_f32_e32 v36, v39, v9
	ds_read_b128 v[32:35], v63 offset:928
	v_fmac_f32_e32 v36, v38, v7
	v_add_f32_e32 v36, v37, v36
	v_add_f32_e32 v41, v41, v36
	ds_read_b128 v[36:39], v63 offset:944
	s_waitcnt lgkmcnt(1)
	v_mul_f32_e32 v33, v33, v4
	v_fmac_f32_e32 v33, v32, v3
	v_mul_f32_e32 v32, v35, v6
	v_fmac_f32_e32 v32, v34, v5
	v_add_f32_e32 v32, v33, v32
	s_waitcnt lgkmcnt(0)
	v_mul_f32_e32 v33, v37, v16
	v_mul_f32_e32 v34, v39, v15
	v_fmac_f32_e32 v33, v36, v14
	v_fmac_f32_e32 v34, v38, v13
	v_add_f32_e32 v32, v41, v32
	v_add_f32_e32 v33, v33, v34
	v_add_f32_e32 v33, v32, v33
	v_mul_f32_e64 v32, |v33|, s64
	v_exp_f32_e32 v38, v32
	ds_read_b128 v[34:37], v63 offset:960
	v_fmamk_f32 v32, v40, 0x3d800000, v31
	v_min_f32_e32 v33, 0, v33
	v_add_f32_e32 v38, 1.0, v38
	v_log_f32_e32 v42, v38
	ds_read_b128 v[38:41], v63 offset:976
	s_waitcnt lgkmcnt(1)
	v_mul_f32_e32 v35, v35, v2
	v_fmac_f32_e32 v35, v34, v17
	v_mul_f32_e32 v34, v37, v12
	v_fmac_f32_e32 v34, v36, v10
	v_add_f32_e32 v34, v35, v34
	s_waitcnt lgkmcnt(0)
	v_mul_f32_e32 v39, v39, v11
	v_add_f32_e32 v43, v18, v34
	v_fmac_f32_e32 v39, v38, v8
	v_mul_f32_e32 v38, v41, v9
	ds_read_b128 v[34:37], v63 offset:992
	v_fmac_f32_e32 v38, v40, v7
	v_add_f32_e32 v38, v39, v38
	v_add_f32_e32 v43, v43, v38
	ds_read_b128 v[38:41], v63 offset:1008
	s_waitcnt lgkmcnt(1)
	v_mul_f32_e32 v35, v35, v4
	v_fmac_f32_e32 v35, v34, v3
	v_mul_f32_e32 v34, v37, v6
	v_fmac_f32_e32 v34, v36, v5
	v_add_f32_e32 v34, v35, v34
	s_waitcnt lgkmcnt(0)
	v_mul_f32_e32 v35, v39, v16
	v_mul_f32_e32 v36, v41, v15
	v_fmac_f32_e32 v35, v38, v14
	v_fmac_f32_e32 v36, v40, v13
	v_add_f32_e32 v34, v43, v34
	v_add_f32_e32 v35, v35, v36
	v_add_f32_e32 v43, v34, v35
	v_mul_f32_e64 v34, |v43|, s64
	v_exp_f32_e32 v38, v34
	ds_read_b128 v[34:37], v63 offset:1024
	v_fmac_f32_e32 v33, 0xbf317218, v42
	v_min_f32_e32 v43, 0, v43
	v_add_f32_e32 v38, 1.0, v38
	v_log_f32_e32 v42, v38
	ds_read_b128 v[38:41], v63 offset:1040
	s_waitcnt lgkmcnt(1)
	v_mul_f32_e32 v35, v35, v2
	v_fmac_f32_e32 v35, v34, v17
	v_mul_f32_e32 v34, v37, v12
	v_fmac_f32_e32 v34, v36, v10
	v_add_f32_e32 v34, v35, v34
	s_waitcnt lgkmcnt(0)
	v_mul_f32_e32 v39, v39, v11
	v_add_f32_e32 v44, v18, v34
	v_fmac_f32_e32 v39, v38, v8
	v_mul_f32_e32 v38, v41, v9
	ds_read_b128 v[34:37], v63 offset:1056
	v_fmac_f32_e32 v38, v40, v7
	v_add_f32_e32 v38, v39, v38
	v_add_f32_e32 v44, v44, v38
	ds_read_b128 v[38:41], v63 offset:1072
	s_waitcnt lgkmcnt(1)
	v_mul_f32_e32 v35, v35, v4
	v_fmac_f32_e32 v35, v34, v3
	v_mul_f32_e32 v34, v37, v6
	v_fmac_f32_e32 v34, v36, v5
	v_add_f32_e32 v34, v35, v34
	s_waitcnt lgkmcnt(0)
	v_mul_f32_e32 v35, v39, v16
	v_mul_f32_e32 v36, v41, v15
	v_fmac_f32_e32 v35, v38, v14
	v_fmac_f32_e32 v36, v40, v13
	v_add_f32_e32 v34, v44, v34
	v_add_f32_e32 v35, v35, v36
	v_add_f32_e32 v44, v34, v35
	v_mul_f32_e64 v34, |v44|, s64
	v_exp_f32_e32 v38, v34
	ds_read_b128 v[34:37], v63 offset:1088
	v_fmac_f32_e32 v43, 0xbf317218, v42
	v_fmamk_f32 v33, v33, 0x3d800000, v32
	v_add_f32_e32 v38, 1.0, v38
	v_log_f32_e32 v42, v38
	ds_read_b128 v[38:41], v63 offset:1104
	s_waitcnt lgkmcnt(1)
	v_mul_f32_e32 v35, v35, v2
	v_fmac_f32_e32 v35, v34, v17
	v_mul_f32_e32 v34, v37, v12
	v_fmac_f32_e32 v34, v36, v10
	v_add_f32_e32 v34, v35, v34
	s_waitcnt lgkmcnt(0)
	v_mul_f32_e32 v39, v39, v11
	v_add_f32_e32 v45, v18, v34
	v_fmac_f32_e32 v39, v38, v8
	v_mul_f32_e32 v38, v41, v9
	ds_read_b128 v[34:37], v63 offset:1120
	v_fmac_f32_e32 v38, v40, v7
	v_add_f32_e32 v38, v39, v38
	v_add_f32_e32 v45, v45, v38
	ds_read_b128 v[38:41], v63 offset:1136
	s_waitcnt lgkmcnt(1)
	v_mul_f32_e32 v35, v35, v4
	v_fmac_f32_e32 v35, v34, v3
	v_mul_f32_e32 v34, v37, v6
	v_fmac_f32_e32 v34, v36, v5
	v_add_f32_e32 v34, v35, v34
	s_waitcnt lgkmcnt(0)
	v_mul_f32_e32 v35, v39, v16
	v_mul_f32_e32 v36, v41, v15
	v_fmac_f32_e32 v35, v38, v14
	v_fmac_f32_e32 v36, v40, v13
	v_add_f32_e32 v34, v45, v34
	v_add_f32_e32 v35, v35, v36
	v_add_f32_e32 v40, v34, v35
	v_mul_f32_e64 v34, |v40|, s64
	v_exp_f32_e32 v35, v34
	v_min_f32_e32 v41, 0, v44
	v_fmac_f32_e32 v41, 0xbf317218, v42
	ds_read_b128 v[36:39], v63 offset:1152
	v_add_f32_e32 v35, 1.0, v35
	v_log_f32_e32 v42, v35
	v_fmamk_f32 v34, v43, 0x3d800000, v33
	v_min_f32_e32 v44, 0, v40
	v_fmamk_f32 v35, v41, 0x3d800000, v34
	v_fmac_f32_e32 v44, 0xbf317218, v42
	ds_read_b128 v[40:43], v63 offset:1168
	s_waitcnt lgkmcnt(1)
	v_mul_f32_e32 v37, v37, v2
	v_fmac_f32_e32 v37, v36, v17
	v_mul_f32_e32 v36, v39, v12
	v_fmac_f32_e32 v36, v38, v10
	v_add_f32_e32 v36, v37, v36
	s_waitcnt lgkmcnt(0)
	v_mul_f32_e32 v41, v41, v11
	v_add_f32_e32 v45, v18, v36
	v_fmac_f32_e32 v41, v40, v8
	v_mul_f32_e32 v40, v43, v9
	ds_read_b128 v[36:39], v63 offset:1184
	v_fmac_f32_e32 v40, v42, v7
	v_add_f32_e32 v40, v41, v40
	v_add_f32_e32 v45, v45, v40
	ds_read_b128 v[40:43], v63 offset:1200
	s_waitcnt lgkmcnt(1)
	v_mul_f32_e32 v37, v37, v4
	v_fmac_f32_e32 v37, v36, v3
	v_mul_f32_e32 v36, v39, v6
	v_fmac_f32_e32 v36, v38, v5
	v_add_f32_e32 v36, v37, v36
	s_waitcnt lgkmcnt(0)
	v_mul_f32_e32 v37, v41, v16
	v_mul_f32_e32 v38, v43, v15
	v_fmac_f32_e32 v37, v40, v14
	v_fmac_f32_e32 v38, v42, v13
	v_add_f32_e32 v36, v45, v36
	v_add_f32_e32 v37, v37, v38
	v_add_f32_e32 v37, v36, v37
	v_mul_f32_e64 v36, |v37|, s64
	v_exp_f32_e32 v42, v36
	ds_read_b128 v[38:41], v63 offset:1216
	v_fmamk_f32 v36, v44, 0x3d800000, v35
	v_min_f32_e32 v37, 0, v37
	v_add_f32_e32 v42, 1.0, v42
	v_log_f32_e32 v46, v42
	ds_read_b128 v[42:45], v63 offset:1232
	s_waitcnt lgkmcnt(1)
	v_mul_f32_e32 v39, v39, v2
	v_fmac_f32_e32 v39, v38, v17
	v_mul_f32_e32 v38, v41, v12
	v_fmac_f32_e32 v38, v40, v10
	v_add_f32_e32 v38, v39, v38
	s_waitcnt lgkmcnt(0)
	v_mul_f32_e32 v43, v43, v11
	v_add_f32_e32 v47, v18, v38
	v_fmac_f32_e32 v43, v42, v8
	v_mul_f32_e32 v42, v45, v9
	ds_read_b128 v[38:41], v63 offset:1248
	v_fmac_f32_e32 v42, v44, v7
	v_add_f32_e32 v42, v43, v42
	v_add_f32_e32 v47, v47, v42
	ds_read_b128 v[42:45], v63 offset:1264
	s_waitcnt lgkmcnt(1)
	v_mul_f32_e32 v39, v39, v4
	v_fmac_f32_e32 v39, v38, v3
	v_mul_f32_e32 v38, v41, v6
	v_fmac_f32_e32 v38, v40, v5
	v_add_f32_e32 v38, v39, v38
	s_waitcnt lgkmcnt(0)
	v_mul_f32_e32 v39, v43, v16
	v_mul_f32_e32 v40, v45, v15
	v_fmac_f32_e32 v39, v42, v14
	v_fmac_f32_e32 v40, v44, v13
	v_add_f32_e32 v38, v47, v38
	v_add_f32_e32 v39, v39, v40
	v_add_f32_e32 v47, v38, v39
	v_mul_f32_e64 v38, |v47|, s64
	v_exp_f32_e32 v42, v38
	ds_read_b128 v[38:41], v63 offset:1280
	v_fmac_f32_e32 v37, 0xbf317218, v46
	v_min_f32_e32 v47, 0, v47
	v_add_f32_e32 v42, 1.0, v42
	v_log_f32_e32 v46, v42
	ds_read_b128 v[42:45], v63 offset:1296
	s_waitcnt lgkmcnt(1)
	v_mul_f32_e32 v39, v39, v2
	v_fmac_f32_e32 v39, v38, v17
	v_mul_f32_e32 v38, v41, v12
	v_fmac_f32_e32 v38, v40, v10
	v_add_f32_e32 v38, v39, v38
	s_waitcnt lgkmcnt(0)
	v_mul_f32_e32 v43, v43, v11
	v_add_f32_e32 v48, v18, v38
	v_fmac_f32_e32 v43, v42, v8
	v_mul_f32_e32 v42, v45, v9
	ds_read_b128 v[38:41], v63 offset:1312
	v_fmac_f32_e32 v42, v44, v7
	v_add_f32_e32 v42, v43, v42
	v_add_f32_e32 v48, v48, v42
	ds_read_b128 v[42:45], v63 offset:1328
	s_waitcnt lgkmcnt(1)
	v_mul_f32_e32 v39, v39, v4
	v_fmac_f32_e32 v39, v38, v3
	v_mul_f32_e32 v38, v41, v6
	v_fmac_f32_e32 v38, v40, v5
	v_add_f32_e32 v38, v39, v38
	s_waitcnt lgkmcnt(0)
	v_mul_f32_e32 v39, v43, v16
	v_mul_f32_e32 v40, v45, v15
	v_fmac_f32_e32 v39, v42, v14
	v_fmac_f32_e32 v40, v44, v13
	v_add_f32_e32 v38, v48, v38
	v_add_f32_e32 v39, v39, v40
	v_add_f32_e32 v48, v38, v39
	v_mul_f32_e64 v38, |v48|, s64
	v_exp_f32_e32 v42, v38
	ds_read_b128 v[38:41], v63 offset:1344
	v_fmac_f32_e32 v47, 0xbf317218, v46
	v_fmamk_f32 v37, v37, 0x3d800000, v36
	v_add_f32_e32 v42, 1.0, v42
	v_log_f32_e32 v46, v42
	ds_read_b128 v[42:45], v63 offset:1360
	s_waitcnt lgkmcnt(1)
	v_mul_f32_e32 v39, v39, v2
	v_fmac_f32_e32 v39, v38, v17
	v_mul_f32_e32 v38, v41, v12
	v_fmac_f32_e32 v38, v40, v10
	v_add_f32_e32 v38, v39, v38
	s_waitcnt lgkmcnt(0)
	v_mul_f32_e32 v43, v43, v11
	v_add_f32_e32 v49, v18, v38
	v_fmac_f32_e32 v43, v42, v8
	v_mul_f32_e32 v42, v45, v9
	ds_read_b128 v[38:41], v63 offset:1376
	v_fmac_f32_e32 v42, v44, v7
	v_add_f32_e32 v42, v43, v42
	v_add_f32_e32 v49, v49, v42
	ds_read_b128 v[42:45], v63 offset:1392
	s_waitcnt lgkmcnt(1)
	v_mul_f32_e32 v39, v39, v4
	v_fmac_f32_e32 v39, v38, v3
	v_mul_f32_e32 v38, v41, v6
	v_fmac_f32_e32 v38, v40, v5
	v_add_f32_e32 v38, v39, v38
	s_waitcnt lgkmcnt(0)
	v_mul_f32_e32 v39, v43, v16
	v_mul_f32_e32 v40, v45, v15
	v_fmac_f32_e32 v39, v42, v14
	v_fmac_f32_e32 v40, v44, v13
	v_add_f32_e32 v38, v49, v38
	v_add_f32_e32 v39, v39, v40
	v_add_f32_e32 v44, v38, v39
	v_mul_f32_e64 v38, |v44|, s64
	v_exp_f32_e32 v39, v38
	v_min_f32_e32 v45, 0, v48
	v_fmac_f32_e32 v45, 0xbf317218, v46
	ds_read_b128 v[40:43], v63 offset:1408
	v_add_f32_e32 v39, 1.0, v39
	v_log_f32_e32 v46, v39
	v_fmamk_f32 v38, v47, 0x3d800000, v37
	v_min_f32_e32 v48, 0, v44
	v_fmamk_f32 v39, v45, 0x3d800000, v38
	v_fmac_f32_e32 v48, 0xbf317218, v46
	ds_read_b128 v[44:47], v63 offset:1424
	s_waitcnt lgkmcnt(1)
	v_mul_f32_e32 v41, v41, v2
	v_fmac_f32_e32 v41, v40, v17
	v_mul_f32_e32 v40, v43, v12
	v_fmac_f32_e32 v40, v42, v10
	v_add_f32_e32 v40, v41, v40
	s_waitcnt lgkmcnt(0)
	v_mul_f32_e32 v45, v45, v11
	v_add_f32_e32 v49, v18, v40
	v_fmac_f32_e32 v45, v44, v8
	v_mul_f32_e32 v44, v47, v9
	ds_read_b128 v[40:43], v63 offset:1440
	v_fmac_f32_e32 v44, v46, v7
	v_add_f32_e32 v44, v45, v44
	v_add_f32_e32 v49, v49, v44
	ds_read_b128 v[44:47], v63 offset:1456
	s_waitcnt lgkmcnt(1)
	v_mul_f32_e32 v41, v41, v4
	v_fmac_f32_e32 v41, v40, v3
	v_mul_f32_e32 v40, v43, v6
	v_fmac_f32_e32 v40, v42, v5
	v_add_f32_e32 v40, v41, v40
	s_waitcnt lgkmcnt(0)
	v_mul_f32_e32 v41, v45, v16
	v_mul_f32_e32 v42, v47, v15
	v_fmac_f32_e32 v41, v44, v14
	v_fmac_f32_e32 v42, v46, v13
	v_add_f32_e32 v40, v49, v40
	v_add_f32_e32 v41, v41, v42
	v_add_f32_e32 v41, v40, v41
	v_mul_f32_e64 v40, |v41|, s64
	v_exp_f32_e32 v46, v40
	ds_read_b128 v[42:45], v63 offset:1472
	v_fmamk_f32 v40, v48, 0x3d800000, v39
	v_min_f32_e32 v41, 0, v41
	v_add_f32_e32 v46, 1.0, v46
	v_log_f32_e32 v50, v46
	ds_read_b128 v[46:49], v63 offset:1488
	s_waitcnt lgkmcnt(1)
	v_mul_f32_e32 v43, v43, v2
	v_fmac_f32_e32 v43, v42, v17
	v_mul_f32_e32 v42, v45, v12
	v_fmac_f32_e32 v42, v44, v10
	v_add_f32_e32 v42, v43, v42
	s_waitcnt lgkmcnt(0)
	v_mul_f32_e32 v47, v47, v11
	v_add_f32_e32 v51, v18, v42
	v_fmac_f32_e32 v47, v46, v8
	v_mul_f32_e32 v46, v49, v9
	ds_read_b128 v[42:45], v63 offset:1504
	v_fmac_f32_e32 v46, v48, v7
	v_add_f32_e32 v46, v47, v46
	v_add_f32_e32 v51, v51, v46
	ds_read_b128 v[46:49], v63 offset:1520
	s_waitcnt lgkmcnt(1)
	v_mul_f32_e32 v43, v43, v4
	v_fmac_f32_e32 v43, v42, v3
	v_mul_f32_e32 v42, v45, v6
	v_fmac_f32_e32 v42, v44, v5
	v_add_f32_e32 v42, v43, v42
	s_waitcnt lgkmcnt(0)
	v_mul_f32_e32 v43, v47, v16
	v_mul_f32_e32 v44, v49, v15
	v_fmac_f32_e32 v43, v46, v14
	v_fmac_f32_e32 v44, v48, v13
	v_add_f32_e32 v42, v51, v42
	v_add_f32_e32 v43, v43, v44
	v_add_f32_e32 v51, v42, v43
	v_mul_f32_e64 v42, |v51|, s64
	v_exp_f32_e32 v46, v42
	ds_read_b128 v[42:45], v63 offset:1536
	v_fmac_f32_e32 v41, 0xbf317218, v50
	v_min_f32_e32 v51, 0, v51
	v_add_f32_e32 v46, 1.0, v46
	v_log_f32_e32 v50, v46
	ds_read_b128 v[46:49], v63 offset:1552
	s_waitcnt lgkmcnt(1)
	v_mul_f32_e32 v43, v43, v2
	v_fmac_f32_e32 v43, v42, v17
	v_mul_f32_e32 v42, v45, v12
	v_fmac_f32_e32 v42, v44, v10
	v_add_f32_e32 v42, v43, v42
	s_waitcnt lgkmcnt(0)
	v_mul_f32_e32 v47, v47, v11
	v_add_f32_e32 v52, v18, v42
	v_fmac_f32_e32 v47, v46, v8
	v_mul_f32_e32 v46, v49, v9
	ds_read_b128 v[42:45], v63 offset:1568
	v_fmac_f32_e32 v46, v48, v7
	v_add_f32_e32 v46, v47, v46
	v_add_f32_e32 v52, v52, v46
	ds_read_b128 v[46:49], v63 offset:1584
	s_waitcnt lgkmcnt(1)
	v_mul_f32_e32 v43, v43, v4
	v_fmac_f32_e32 v43, v42, v3
	v_mul_f32_e32 v42, v45, v6
	v_fmac_f32_e32 v42, v44, v5
	v_add_f32_e32 v42, v43, v42
	s_waitcnt lgkmcnt(0)
	v_mul_f32_e32 v43, v47, v16
	v_mul_f32_e32 v44, v49, v15
	v_fmac_f32_e32 v43, v46, v14
	v_fmac_f32_e32 v44, v48, v13
	v_add_f32_e32 v42, v52, v42
	v_add_f32_e32 v43, v43, v44
	v_add_f32_e32 v52, v42, v43
	v_mul_f32_e64 v42, |v52|, s64
	v_exp_f32_e32 v46, v42
	ds_read_b128 v[42:45], v63 offset:1600
	v_fmac_f32_e32 v51, 0xbf317218, v50
	v_fmamk_f32 v41, v41, 0x3d800000, v40
	v_add_f32_e32 v46, 1.0, v46
	v_log_f32_e32 v50, v46
	ds_read_b128 v[46:49], v63 offset:1616
	s_waitcnt lgkmcnt(1)
	v_mul_f32_e32 v43, v43, v2
	v_fmac_f32_e32 v43, v42, v17
	v_mul_f32_e32 v42, v45, v12
	v_fmac_f32_e32 v42, v44, v10
	v_add_f32_e32 v42, v43, v42
	s_waitcnt lgkmcnt(0)
	v_mul_f32_e32 v47, v47, v11
	v_add_f32_e32 v53, v18, v42
	v_fmac_f32_e32 v47, v46, v8
	v_mul_f32_e32 v46, v49, v9
	ds_read_b128 v[42:45], v63 offset:1632
	v_fmac_f32_e32 v46, v48, v7
	v_add_f32_e32 v46, v47, v46
	v_add_f32_e32 v53, v53, v46
	ds_read_b128 v[46:49], v63 offset:1648
	s_waitcnt lgkmcnt(1)
	v_mul_f32_e32 v43, v43, v4
	v_fmac_f32_e32 v43, v42, v3
	v_mul_f32_e32 v42, v45, v6
	v_fmac_f32_e32 v42, v44, v5
	v_add_f32_e32 v42, v43, v42
	s_waitcnt lgkmcnt(0)
	v_mul_f32_e32 v43, v47, v16
	v_mul_f32_e32 v44, v49, v15
	v_fmac_f32_e32 v43, v46, v14
	v_fmac_f32_e32 v44, v48, v13
	v_add_f32_e32 v42, v53, v42
	v_add_f32_e32 v43, v43, v44
	v_add_f32_e32 v48, v42, v43
	v_mul_f32_e64 v42, |v48|, s64
	v_exp_f32_e32 v43, v42
	v_min_f32_e32 v49, 0, v52
	v_fmac_f32_e32 v49, 0xbf317218, v50
	ds_read_b128 v[44:47], v63 offset:1664
	v_add_f32_e32 v43, 1.0, v43
	v_log_f32_e32 v50, v43
	v_fmamk_f32 v42, v51, 0x3d800000, v41
	v_min_f32_e32 v52, 0, v48
	v_fmamk_f32 v43, v49, 0x3d800000, v42
	v_fmac_f32_e32 v52, 0xbf317218, v50
	ds_read_b128 v[48:51], v63 offset:1680
	s_waitcnt lgkmcnt(1)
	v_mul_f32_e32 v45, v45, v2
	v_fmac_f32_e32 v45, v44, v17
	v_mul_f32_e32 v44, v47, v12
	v_fmac_f32_e32 v44, v46, v10
	v_add_f32_e32 v44, v45, v44
	s_waitcnt lgkmcnt(0)
	v_mul_f32_e32 v49, v49, v11
	v_add_f32_e32 v53, v18, v44
	v_fmac_f32_e32 v49, v48, v8
	v_mul_f32_e32 v48, v51, v9
	ds_read_b128 v[44:47], v63 offset:1696
	v_fmac_f32_e32 v48, v50, v7
	v_add_f32_e32 v48, v49, v48
	v_add_f32_e32 v53, v53, v48
	ds_read_b128 v[48:51], v63 offset:1712
	s_waitcnt lgkmcnt(1)
	v_mul_f32_e32 v45, v45, v4
	v_fmac_f32_e32 v45, v44, v3
	v_mul_f32_e32 v44, v47, v6
	v_fmac_f32_e32 v44, v46, v5
	v_add_f32_e32 v44, v45, v44
	s_waitcnt lgkmcnt(0)
	v_mul_f32_e32 v45, v49, v16
	v_mul_f32_e32 v46, v51, v15
	v_fmac_f32_e32 v45, v48, v14
	v_fmac_f32_e32 v46, v50, v13
	v_add_f32_e32 v44, v53, v44
	v_add_f32_e32 v45, v45, v46
	v_add_f32_e32 v45, v44, v45
	v_mul_f32_e64 v44, |v45|, s64
	v_exp_f32_e32 v50, v44
	ds_read_b128 v[46:49], v63 offset:1728
	v_fmamk_f32 v44, v52, 0x3d800000, v43
	v_min_f32_e32 v45, 0, v45
	v_add_f32_e32 v50, 1.0, v50
	v_log_f32_e32 v54, v50
	ds_read_b128 v[50:53], v63 offset:1744
	s_waitcnt lgkmcnt(1)
	v_mul_f32_e32 v47, v47, v2
	v_fmac_f32_e32 v47, v46, v17
	v_mul_f32_e32 v46, v49, v12
	v_fmac_f32_e32 v46, v48, v10
	v_add_f32_e32 v46, v47, v46
	s_waitcnt lgkmcnt(0)
	v_mul_f32_e32 v51, v51, v11
	v_add_f32_e32 v55, v18, v46
	v_fmac_f32_e32 v51, v50, v8
	v_mul_f32_e32 v50, v53, v9
	ds_read_b128 v[46:49], v63 offset:1760
	v_fmac_f32_e32 v50, v52, v7
	v_add_f32_e32 v50, v51, v50
	v_add_f32_e32 v55, v55, v50
	ds_read_b128 v[50:53], v63 offset:1776
	s_waitcnt lgkmcnt(1)
	v_mul_f32_e32 v47, v47, v4
	v_fmac_f32_e32 v47, v46, v3
	v_mul_f32_e32 v46, v49, v6
	v_fmac_f32_e32 v46, v48, v5
	v_add_f32_e32 v46, v47, v46
	s_waitcnt lgkmcnt(0)
	v_mul_f32_e32 v47, v51, v16
	v_mul_f32_e32 v48, v53, v15
	v_fmac_f32_e32 v47, v50, v14
	v_fmac_f32_e32 v48, v52, v13
	v_add_f32_e32 v46, v55, v46
	v_add_f32_e32 v47, v47, v48
	v_add_f32_e32 v55, v46, v47
	v_mul_f32_e64 v46, |v55|, s64
	v_exp_f32_e32 v50, v46
	ds_read_b128 v[46:49], v63 offset:1792
	v_fmac_f32_e32 v45, 0xbf317218, v54
	v_min_f32_e32 v55, 0, v55
	v_add_f32_e32 v50, 1.0, v50
	v_log_f32_e32 v54, v50
	ds_read_b128 v[50:53], v63 offset:1808
	s_waitcnt lgkmcnt(1)
	v_mul_f32_e32 v47, v47, v2
	v_fmac_f32_e32 v47, v46, v17
	v_mul_f32_e32 v46, v49, v12
	v_fmac_f32_e32 v46, v48, v10
	v_add_f32_e32 v46, v47, v46
	s_waitcnt lgkmcnt(0)
	v_mul_f32_e32 v51, v51, v11
	v_add_f32_e32 v56, v18, v46
	v_fmac_f32_e32 v51, v50, v8
	v_mul_f32_e32 v50, v53, v9
	ds_read_b128 v[46:49], v63 offset:1824
	v_fmac_f32_e32 v50, v52, v7
	v_add_f32_e32 v50, v51, v50
	v_add_f32_e32 v56, v56, v50
	ds_read_b128 v[50:53], v63 offset:1840
	s_waitcnt lgkmcnt(1)
	v_mul_f32_e32 v47, v47, v4
	v_fmac_f32_e32 v47, v46, v3
	v_mul_f32_e32 v46, v49, v6
	v_fmac_f32_e32 v46, v48, v5
	v_add_f32_e32 v46, v47, v46
	s_waitcnt lgkmcnt(0)
	v_mul_f32_e32 v47, v51, v16
	v_mul_f32_e32 v48, v53, v15
	v_fmac_f32_e32 v47, v50, v14
	v_fmac_f32_e32 v48, v52, v13
	v_add_f32_e32 v46, v56, v46
	v_add_f32_e32 v47, v47, v48
	v_add_f32_e32 v56, v46, v47
	v_mul_f32_e64 v46, |v56|, s64
	v_exp_f32_e32 v50, v46
	ds_read_b128 v[46:49], v63 offset:1856
	v_fmac_f32_e32 v55, 0xbf317218, v54
	v_fmamk_f32 v45, v45, 0x3d800000, v44
	v_add_f32_e32 v50, 1.0, v50
	v_log_f32_e32 v54, v50
	ds_read_b128 v[50:53], v63 offset:1872
	s_waitcnt lgkmcnt(1)
	v_mul_f32_e32 v47, v47, v2
	v_fmac_f32_e32 v47, v46, v17
	v_mul_f32_e32 v46, v49, v12
	v_fmac_f32_e32 v46, v48, v10
	v_add_f32_e32 v46, v47, v46
	s_waitcnt lgkmcnt(0)
	v_mul_f32_e32 v51, v51, v11
	v_add_f32_e32 v57, v18, v46
	v_fmac_f32_e32 v51, v50, v8
	v_mul_f32_e32 v50, v53, v9
	ds_read_b128 v[46:49], v63 offset:1888
	v_fmac_f32_e32 v50, v52, v7
	v_add_f32_e32 v50, v51, v50
	v_add_f32_e32 v57, v57, v50
	ds_read_b128 v[50:53], v63 offset:1904
	s_waitcnt lgkmcnt(1)
	v_mul_f32_e32 v47, v47, v4
	v_fmac_f32_e32 v47, v46, v3
	v_mul_f32_e32 v46, v49, v6
	v_fmac_f32_e32 v46, v48, v5
	v_add_f32_e32 v46, v47, v46
	s_waitcnt lgkmcnt(0)
	v_mul_f32_e32 v47, v51, v16
	v_mul_f32_e32 v48, v53, v15
	v_fmac_f32_e32 v47, v50, v14
	v_fmac_f32_e32 v48, v52, v13
	v_add_f32_e32 v46, v57, v46
	v_add_f32_e32 v47, v47, v48
	v_add_f32_e32 v52, v46, v47
	v_mul_f32_e64 v46, |v52|, s64
	v_exp_f32_e32 v47, v46
	v_min_f32_e32 v53, 0, v56
	v_fmac_f32_e32 v53, 0xbf317218, v54
	ds_read_b128 v[48:51], v63 offset:1920
	v_add_f32_e32 v47, 1.0, v47
	v_log_f32_e32 v54, v47
	v_fmamk_f32 v46, v55, 0x3d800000, v45
	v_min_f32_e32 v56, 0, v52
	v_fmamk_f32 v47, v53, 0x3d800000, v46
	v_fmac_f32_e32 v56, 0xbf317218, v54
	ds_read_b128 v[52:55], v63 offset:1936
	s_waitcnt lgkmcnt(1)
	v_mul_f32_e32 v49, v49, v2
	v_fmac_f32_e32 v49, v48, v17
	v_mul_f32_e32 v48, v51, v12
	v_fmac_f32_e32 v48, v50, v10
	v_add_f32_e32 v48, v49, v48
	s_waitcnt lgkmcnt(0)
	v_mul_f32_e32 v53, v53, v11
	v_add_f32_e32 v57, v18, v48
	v_fmac_f32_e32 v53, v52, v8
	v_mul_f32_e32 v52, v55, v9
	ds_read_b128 v[48:51], v63 offset:1952
	v_fmac_f32_e32 v52, v54, v7
	v_add_f32_e32 v52, v53, v52
	v_add_f32_e32 v57, v57, v52
	ds_read_b128 v[52:55], v63 offset:1968
	s_waitcnt lgkmcnt(1)
	v_mul_f32_e32 v49, v49, v4
	v_fmac_f32_e32 v49, v48, v3
	v_mul_f32_e32 v48, v51, v6
	v_fmac_f32_e32 v48, v50, v5
	v_add_f32_e32 v48, v49, v48
	s_waitcnt lgkmcnt(0)
	v_mul_f32_e32 v49, v53, v16
	v_mul_f32_e32 v50, v55, v15
	v_fmac_f32_e32 v49, v52, v14
	v_fmac_f32_e32 v50, v54, v13
	v_add_f32_e32 v48, v57, v48
	v_add_f32_e32 v49, v49, v50
	v_add_f32_e32 v49, v48, v49
	v_mul_f32_e64 v48, |v49|, s64
	v_exp_f32_e32 v54, v48
	ds_read_b128 v[50:53], v63 offset:1984
	v_fmamk_f32 v48, v56, 0x3d800000, v47
	v_min_f32_e32 v49, 0, v49
	v_add_f32_e32 v54, 1.0, v54
	v_log_f32_e32 v58, v54
	ds_read_b128 v[54:57], v63 offset:2000
	s_waitcnt lgkmcnt(1)
	v_mul_f32_e32 v51, v51, v2
	v_fmac_f32_e32 v51, v50, v17
	v_mul_f32_e32 v50, v53, v12
	v_fmac_f32_e32 v50, v52, v10
	v_add_f32_e32 v50, v51, v50
	s_waitcnt lgkmcnt(0)
	v_mul_f32_e32 v55, v55, v11
	v_add_f32_e32 v59, v18, v50
	v_fmac_f32_e32 v55, v54, v8
	v_mul_f32_e32 v54, v57, v9
	ds_read_b128 v[50:53], v63 offset:2016
	v_fmac_f32_e32 v54, v56, v7
	v_add_f32_e32 v54, v55, v54
	v_add_f32_e32 v59, v59, v54
	ds_read_b128 v[54:57], v63 offset:2032
	s_waitcnt lgkmcnt(1)
	v_mul_f32_e32 v51, v51, v4
	v_fmac_f32_e32 v51, v50, v3
	v_mul_f32_e32 v50, v53, v6
	v_fmac_f32_e32 v50, v52, v5
	v_add_f32_e32 v50, v51, v50
	s_waitcnt lgkmcnt(0)
	v_mul_f32_e32 v51, v55, v16
	v_mul_f32_e32 v52, v57, v15
	v_fmac_f32_e32 v51, v54, v14
	v_fmac_f32_e32 v52, v56, v13
	v_add_f32_e32 v50, v59, v50
	v_add_f32_e32 v51, v51, v52
	v_add_f32_e32 v59, v50, v51
	v_mul_f32_e64 v50, |v59|, s64
	v_exp_f32_e32 v54, v50
	ds_read_b128 v[50:53], v63 offset:2048
	v_fmac_f32_e32 v49, 0xbf317218, v58
	v_min_f32_e32 v59, 0, v59
	v_add_f32_e32 v54, 1.0, v54
	v_log_f32_e32 v58, v54
	ds_read_b128 v[54:57], v63 offset:2064
	s_waitcnt lgkmcnt(1)
	v_mul_f32_e32 v51, v51, v2
	v_fmac_f32_e32 v51, v50, v17
	v_mul_f32_e32 v50, v53, v12
	v_fmac_f32_e32 v50, v52, v10
	v_add_f32_e32 v50, v51, v50
	s_waitcnt lgkmcnt(0)
	v_mul_f32_e32 v55, v55, v11
	v_add_f32_e32 v60, v18, v50
	v_fmac_f32_e32 v55, v54, v8
	v_mul_f32_e32 v54, v57, v9
	ds_read_b128 v[50:53], v63 offset:2080
	v_fmac_f32_e32 v54, v56, v7
	v_add_f32_e32 v54, v55, v54
	v_add_f32_e32 v60, v60, v54
	ds_read_b128 v[54:57], v63 offset:2096
	s_waitcnt lgkmcnt(1)
	v_mul_f32_e32 v51, v51, v4
	v_fmac_f32_e32 v51, v50, v3
	v_mul_f32_e32 v50, v53, v6
	v_fmac_f32_e32 v50, v52, v5
	v_add_f32_e32 v50, v51, v50
	s_waitcnt lgkmcnt(0)
	v_mul_f32_e32 v51, v55, v16
	v_mul_f32_e32 v52, v57, v15
	v_fmac_f32_e32 v51, v54, v14
	v_fmac_f32_e32 v52, v56, v13
	v_add_f32_e32 v50, v60, v50
	v_add_f32_e32 v51, v51, v52
	v_add_f32_e32 v60, v50, v51
	v_mul_f32_e64 v50, |v60|, s64
	v_exp_f32_e32 v54, v50
	ds_read_b128 v[50:53], v63 offset:2112
	v_fmac_f32_e32 v59, 0xbf317218, v58
	v_fmamk_f32 v49, v49, 0x3d800000, v48
	v_add_f32_e32 v54, 1.0, v54
	v_log_f32_e32 v58, v54
	ds_read_b128 v[54:57], v63 offset:2128
	s_waitcnt lgkmcnt(1)
	v_mul_f32_e32 v51, v51, v2
	v_fmac_f32_e32 v51, v50, v17
	v_mul_f32_e32 v50, v53, v12
	v_fmac_f32_e32 v50, v52, v10
	v_add_f32_e32 v50, v51, v50
	s_waitcnt lgkmcnt(0)
	v_mul_f32_e32 v55, v55, v11
	v_add_f32_e32 v61, v18, v50
	v_fmac_f32_e32 v55, v54, v8
	v_mul_f32_e32 v54, v57, v9
	ds_read_b128 v[50:53], v63 offset:2144
	v_fmac_f32_e32 v54, v56, v7
	v_add_f32_e32 v54, v55, v54
	v_add_f32_e32 v61, v61, v54
	ds_read_b128 v[54:57], v63 offset:2160
	s_waitcnt lgkmcnt(1)
	v_mul_f32_e32 v51, v51, v4
	v_fmac_f32_e32 v51, v50, v3
	v_mul_f32_e32 v50, v53, v6
	v_fmac_f32_e32 v50, v52, v5
	v_add_f32_e32 v50, v51, v50
	s_waitcnt lgkmcnt(0)
	v_mul_f32_e32 v51, v55, v16
	v_mul_f32_e32 v52, v57, v15
	v_fmac_f32_e32 v51, v54, v14
	v_fmac_f32_e32 v52, v56, v13
	v_add_f32_e32 v50, v61, v50
	v_add_f32_e32 v51, v51, v52
	v_add_f32_e32 v56, v50, v51
	v_mul_f32_e64 v50, |v56|, s64
	v_exp_f32_e32 v51, v50
	v_min_f32_e32 v57, 0, v60
	v_fmac_f32_e32 v57, 0xbf317218, v58
	ds_read_b128 v[52:55], v63 offset:2176
	v_add_f32_e32 v51, 1.0, v51
	v_log_f32_e32 v58, v51
	v_fmamk_f32 v50, v59, 0x3d800000, v49
	v_min_f32_e32 v60, 0, v56
	v_fmamk_f32 v51, v57, 0x3d800000, v50
	v_fmac_f32_e32 v60, 0xbf317218, v58
	ds_read_b128 v[56:59], v63 offset:2192
	s_waitcnt lgkmcnt(1)
	v_mul_f32_e32 v53, v53, v2
	v_fmac_f32_e32 v53, v52, v17
	v_mul_f32_e32 v52, v55, v12
	v_fmac_f32_e32 v52, v54, v10
	v_add_f32_e32 v52, v53, v52
	s_waitcnt lgkmcnt(0)
	v_mul_f32_e32 v57, v57, v11
	v_add_f32_e32 v61, v18, v52
	v_fmac_f32_e32 v57, v56, v8
	v_mul_f32_e32 v56, v59, v9
	ds_read_b128 v[52:55], v63 offset:2208
	v_fmac_f32_e32 v56, v58, v7
	v_add_f32_e32 v56, v57, v56
	v_add_f32_e32 v61, v61, v56
	ds_read_b128 v[56:59], v63 offset:2224
	s_waitcnt lgkmcnt(1)
	v_mul_f32_e32 v53, v53, v4
	v_fmac_f32_e32 v53, v52, v3
	v_mul_f32_e32 v52, v55, v6
	v_fmac_f32_e32 v52, v54, v5
	v_add_f32_e32 v52, v53, v52
	s_waitcnt lgkmcnt(0)
	v_mul_f32_e32 v53, v57, v16
	v_mul_f32_e32 v54, v59, v15
	v_fmac_f32_e32 v53, v56, v14
	v_fmac_f32_e32 v54, v58, v13
	v_add_f32_e32 v52, v61, v52
	v_add_f32_e32 v53, v53, v54
	v_add_f32_e32 v53, v52, v53
	v_mul_f32_e64 v52, |v53|, s64
	v_exp_f32_e32 v58, v52
	ds_read_b128 v[54:57], v63 offset:2240
	v_fmamk_f32 v52, v60, 0x3d800000, v51
	v_min_f32_e32 v53, 0, v53
	v_add_f32_e32 v58, 1.0, v58
	v_log_f32_e32 v64, v58
	ds_read_b128 v[58:61], v63 offset:2256
	s_waitcnt lgkmcnt(1)
	v_mul_f32_e32 v55, v55, v2
	v_fmac_f32_e32 v55, v54, v17
	v_mul_f32_e32 v54, v57, v12
	v_fmac_f32_e32 v54, v56, v10
	v_add_f32_e32 v54, v55, v54
	s_waitcnt lgkmcnt(0)
	v_mul_f32_e32 v59, v59, v11
	v_add_f32_e32 v72, v18, v54
	v_fmac_f32_e32 v59, v58, v8
	v_mul_f32_e32 v58, v61, v9
	ds_read_b128 v[54:57], v63 offset:2272
	v_fmac_f32_e32 v58, v60, v7
	v_add_f32_e32 v58, v59, v58
	v_add_f32_e32 v72, v72, v58
	ds_read_b128 v[58:61], v63 offset:2288
	s_waitcnt lgkmcnt(1)
	v_mul_f32_e32 v55, v55, v4
	v_fmac_f32_e32 v55, v54, v3
	v_mul_f32_e32 v54, v57, v6
	v_fmac_f32_e32 v54, v56, v5
	v_add_f32_e32 v54, v55, v54
	s_waitcnt lgkmcnt(0)
	v_mul_f32_e32 v55, v59, v16
	v_mul_f32_e32 v56, v61, v15
	v_fmac_f32_e32 v55, v58, v14
	v_fmac_f32_e32 v56, v60, v13
	v_add_f32_e32 v54, v72, v54
	v_add_f32_e32 v55, v55, v56
	v_add_f32_e32 v72, v54, v55
	v_mul_f32_e64 v54, |v72|, s64
	v_exp_f32_e32 v58, v54
	ds_read_b128 v[54:57], v63 offset:2304
	v_fmac_f32_e32 v53, 0xbf317218, v64
	v_min_f32_e32 v72, 0, v72
	v_add_f32_e32 v58, 1.0, v58
	v_log_f32_e32 v64, v58
	ds_read_b128 v[58:61], v63 offset:2320
	s_waitcnt lgkmcnt(1)
	v_mul_f32_e32 v55, v55, v2
	v_fmac_f32_e32 v55, v54, v17
	v_mul_f32_e32 v54, v57, v12
	v_fmac_f32_e32 v54, v56, v10
	v_add_f32_e32 v54, v55, v54
	s_waitcnt lgkmcnt(0)
	v_mul_f32_e32 v59, v59, v11
	v_add_f32_e32 v73, v18, v54
	v_fmac_f32_e32 v59, v58, v8
	v_mul_f32_e32 v58, v61, v9
	ds_read_b128 v[54:57], v63 offset:2336
	v_fmac_f32_e32 v58, v60, v7
	v_add_f32_e32 v58, v59, v58
	v_add_f32_e32 v73, v73, v58
	ds_read_b128 v[58:61], v63 offset:2352
	s_waitcnt lgkmcnt(1)
	v_mul_f32_e32 v55, v55, v4
	v_fmac_f32_e32 v55, v54, v3
	v_mul_f32_e32 v54, v57, v6
	v_fmac_f32_e32 v54, v56, v5
	v_add_f32_e32 v54, v55, v54
	s_waitcnt lgkmcnt(0)
	v_mul_f32_e32 v55, v59, v16
	v_mul_f32_e32 v56, v61, v15
	v_fmac_f32_e32 v55, v58, v14
	v_fmac_f32_e32 v56, v60, v13
	v_add_f32_e32 v54, v73, v54
	v_add_f32_e32 v55, v55, v56
	v_add_f32_e32 v73, v54, v55
	v_mul_f32_e64 v54, |v73|, s64
	v_exp_f32_e32 v58, v54
	ds_read_b128 v[54:57], v63 offset:2368
	v_fmac_f32_e32 v72, 0xbf317218, v64
	v_fmamk_f32 v53, v53, 0x3d800000, v52
	v_add_f32_e32 v58, 1.0, v58
	v_log_f32_e32 v64, v58
	ds_read_b128 v[58:61], v63 offset:2384
	s_waitcnt lgkmcnt(1)
	v_mul_f32_e32 v55, v55, v2
	v_fmac_f32_e32 v55, v54, v17
	v_mul_f32_e32 v54, v57, v12
	v_fmac_f32_e32 v54, v56, v10
	v_add_f32_e32 v54, v55, v54
	s_waitcnt lgkmcnt(0)
	v_mul_f32_e32 v59, v59, v11
	v_add_f32_e32 v74, v18, v54
	v_fmac_f32_e32 v59, v58, v8
	v_mul_f32_e32 v58, v61, v9
	ds_read_b128 v[54:57], v63 offset:2400
	v_fmac_f32_e32 v58, v60, v7
	v_add_f32_e32 v58, v59, v58
	v_add_f32_e32 v74, v74, v58
	ds_read_b128 v[58:61], v63 offset:2416
	s_waitcnt lgkmcnt(1)
	v_mul_f32_e32 v55, v55, v4
	v_fmac_f32_e32 v55, v54, v3
	v_mul_f32_e32 v54, v57, v6
	v_fmac_f32_e32 v54, v56, v5
	v_add_f32_e32 v54, v55, v54
	s_waitcnt lgkmcnt(0)
	v_mul_f32_e32 v55, v59, v16
	v_mul_f32_e32 v56, v61, v15
	v_fmac_f32_e32 v55, v58, v14
	v_fmac_f32_e32 v56, v60, v13
	v_add_f32_e32 v54, v74, v54
	v_add_f32_e32 v55, v55, v56
	v_add_f32_e32 v60, v54, v55
	v_mul_f32_e64 v54, |v60|, s64
	v_exp_f32_e32 v55, v54
	ds_read_b128 v[56:59], v63 offset:2432
	v_fmamk_f32 v54, v72, 0x3d800000, v53
	v_min_f32_e32 v61, 0, v73
	v_add_f32_e32 v55, 1.0, v55
	ds_read_b128 v[72:75], v63 offset:2448
	v_fmac_f32_e32 v61, 0xbf317218, v64
	v_log_f32_e32 v64, v55
	s_waitcnt lgkmcnt(1)
	v_mul_f32_e32 v57, v57, v2
	v_fmac_f32_e32 v57, v56, v17
	v_mul_f32_e32 v56, v59, v12
	v_fmac_f32_e32 v56, v58, v10
	v_min_f32_e32 v60, 0, v60
	v_add_f32_e32 v56, v57, v56
	v_fmamk_f32 v55, v61, 0x3d800000, v54
	v_fmac_f32_e32 v60, 0xbf317218, v64
	v_add_f32_e32 v61, v18, v56
	s_waitcnt lgkmcnt(0)
	v_mul_f32_e32 v64, v73, v11
	ds_read_b128 v[56:59], v63 offset:2464
	v_fmac_f32_e32 v64, v72, v8
	v_mul_f32_e32 v72, v75, v9
	v_fmac_f32_e32 v72, v74, v7
	v_add_f32_e32 v64, v64, v72
	ds_read_b128 v[72:75], v63 offset:2480
	s_waitcnt lgkmcnt(1)
	v_mul_f32_e32 v57, v57, v4
	v_fmac_f32_e32 v57, v56, v3
	v_mul_f32_e32 v56, v59, v6
	v_fmac_f32_e32 v56, v58, v5
	v_add_f32_e32 v56, v57, v56
	s_waitcnt lgkmcnt(0)
	v_mul_f32_e32 v57, v73, v16
	v_mul_f32_e32 v58, v75, v15
	v_add_f32_e32 v61, v61, v64
	v_fmac_f32_e32 v57, v72, v14
	v_fmac_f32_e32 v58, v74, v13
	v_add_f32_e32 v56, v61, v56
	v_add_f32_e32 v57, v57, v58
	v_add_f32_e32 v57, v56, v57
	v_mul_f32_e64 v56, |v57|, s64
	v_exp_f32_e32 v64, v56
	v_fmamk_f32 v56, v60, 0x3d800000, v55
	ds_read_b128 v[58:61], v63 offset:2496
	ds_read_b128 v[72:75], v63 offset:2512
	v_add_f32_e32 v64, 1.0, v64
	v_log_f32_e32 v64, v64
	v_min_f32_e32 v57, 0, v57
	s_waitcnt lgkmcnt(1)
	v_mul_f32_e32 v59, v59, v2
	v_fmac_f32_e32 v59, v58, v17
	v_mul_f32_e32 v58, v61, v12
	v_fmac_f32_e32 v58, v60, v10
	v_add_f32_e32 v58, v59, v58
	s_waitcnt lgkmcnt(0)
	v_mul_f32_e32 v73, v73, v11
	v_add_f32_e32 v76, v18, v58
	v_fmac_f32_e32 v73, v72, v8
	v_mul_f32_e32 v72, v75, v9
	ds_read_b128 v[58:61], v63 offset:2528
	v_fmac_f32_e32 v72, v74, v7
	v_add_f32_e32 v72, v73, v72
	v_add_f32_e32 v76, v76, v72
	ds_read_b128 v[72:75], v63 offset:2544
	s_waitcnt lgkmcnt(1)
	v_mul_f32_e32 v59, v59, v4
	v_fmac_f32_e32 v59, v58, v3
	v_mul_f32_e32 v58, v61, v6
	v_fmac_f32_e32 v58, v60, v5
	v_add_f32_e32 v58, v59, v58
	s_waitcnt lgkmcnt(0)
	v_mul_f32_e32 v59, v73, v16
	v_mul_f32_e32 v60, v75, v15
	v_fmac_f32_e32 v59, v72, v14
	v_fmac_f32_e32 v60, v74, v13
	v_add_f32_e32 v58, v76, v58
	v_add_f32_e32 v59, v59, v60
	v_add_f32_e32 v76, v58, v59
	v_mul_f32_e64 v58, |v76|, s64
	v_exp_f32_e32 v72, v58
	ds_read_b128 v[58:61], v63 offset:2560
	v_fmac_f32_e32 v57, 0xbf317218, v64
	v_min_f32_e32 v76, 0, v76
	v_add_f32_e32 v64, 1.0, v72
	ds_read_b128 v[72:75], v63 offset:2576
	s_waitcnt lgkmcnt(1)
	v_mul_f32_e32 v59, v59, v2
	v_fmac_f32_e32 v59, v58, v17
	v_mul_f32_e32 v58, v61, v12
	v_fmac_f32_e32 v58, v60, v10
	v_add_f32_e32 v58, v59, v58
	s_waitcnt lgkmcnt(0)
	v_mul_f32_e32 v73, v73, v11
	v_add_f32_e32 v77, v18, v58
	v_fmac_f32_e32 v73, v72, v8
	v_mul_f32_e32 v72, v75, v9
	ds_read_b128 v[58:61], v63 offset:2592
	v_fmac_f32_e32 v72, v74, v7
	v_add_f32_e32 v72, v73, v72
	v_add_f32_e32 v77, v77, v72
	ds_read_b128 v[72:75], v63 offset:2608
	s_waitcnt lgkmcnt(1)
	v_mul_f32_e32 v59, v59, v4
	v_fmac_f32_e32 v59, v58, v3
	v_mul_f32_e32 v58, v61, v6
	v_fmac_f32_e32 v58, v60, v5
	v_add_f32_e32 v58, v59, v58
	s_waitcnt lgkmcnt(0)
	v_mul_f32_e32 v59, v73, v16
	v_mul_f32_e32 v60, v75, v15
	v_fmac_f32_e32 v59, v72, v14
	v_fmac_f32_e32 v60, v74, v13
	v_add_f32_e32 v58, v77, v58
	v_add_f32_e32 v59, v59, v60
	v_add_f32_e32 v77, v58, v59
	v_mul_f32_e64 v58, |v77|, s64
	v_log_f32_e32 v64, v64
	v_exp_f32_e32 v72, v58
	ds_read_b128 v[58:61], v63 offset:2624
	v_fmamk_f32 v57, v57, 0x3d800000, v56
	v_fmac_f32_e32 v76, 0xbf317218, v64
	v_add_f32_e32 v64, 1.0, v72
	ds_read_b128 v[72:75], v63 offset:2640
	s_waitcnt lgkmcnt(1)
	v_mul_f32_e32 v59, v59, v2
	v_fmac_f32_e32 v59, v58, v17
	v_mul_f32_e32 v58, v61, v12
	v_fmac_f32_e32 v58, v60, v10
	v_add_f32_e32 v58, v59, v58
	s_waitcnt lgkmcnt(0)
	v_mul_f32_e32 v73, v73, v11
	v_add_f32_e32 v78, v18, v58
	v_fmac_f32_e32 v73, v72, v8
	v_mul_f32_e32 v72, v75, v9
	ds_read_b128 v[58:61], v63 offset:2656
	v_fmac_f32_e32 v72, v74, v7
	v_add_f32_e32 v72, v73, v72
	v_add_f32_e32 v78, v78, v72
	ds_read_b128 v[72:75], v63 offset:2672
	s_waitcnt lgkmcnt(1)
	v_mul_f32_e32 v59, v59, v4
	v_fmac_f32_e32 v59, v58, v3
	v_mul_f32_e32 v58, v61, v6
	v_fmac_f32_e32 v58, v60, v5
	v_add_f32_e32 v58, v59, v58
	s_waitcnt lgkmcnt(0)
	v_mul_f32_e32 v59, v73, v16
	v_mul_f32_e32 v60, v75, v15
	v_fmac_f32_e32 v59, v72, v14
	v_fmac_f32_e32 v60, v74, v13
	v_add_f32_e32 v58, v78, v58
	v_add_f32_e32 v59, v59, v60
	v_add_f32_e32 v60, v58, v59
	v_mul_f32_e64 v58, |v60|, s64
	v_exp_f32_e32 v59, v58
	v_log_f32_e32 v64, v64
	v_min_f32_e32 v61, 0, v77
	ds_read_b128 v[72:75], v63 offset:2688
	v_add_f32_e32 v59, 1.0, v59
	v_fmac_f32_e32 v61, 0xbf317218, v64
	v_log_f32_e32 v64, v59
	v_fmamk_f32 v58, v76, 0x3d800000, v57
	ds_read_b128 v[76:79], v63 offset:2704
	v_min_f32_e32 v60, 0, v60
	v_fmamk_f32 v59, v61, 0x3d800000, v58
	v_fmac_f32_e32 v60, 0xbf317218, v64
	s_waitcnt lgkmcnt(1)
	v_mul_f32_e32 v61, v73, v2
	v_mul_f32_e32 v64, v75, v12
	v_fmac_f32_e32 v61, v72, v17
	v_fmac_f32_e32 v64, v74, v10
	ds_read_b128 v[72:75], v63 offset:2720
	v_add_f32_e32 v61, v61, v64
	s_waitcnt lgkmcnt(1)
	v_mul_f32_e32 v64, v77, v11
	v_fmac_f32_e32 v64, v76, v8
	v_mul_f32_e32 v76, v79, v9
	v_fmac_f32_e32 v76, v78, v7
	v_add_f32_e32 v61, v18, v61
	v_add_f32_e32 v64, v64, v76
	ds_read_b128 v[76:79], v63 offset:2736
	v_add_f32_e32 v61, v61, v64
	s_waitcnt lgkmcnt(1)
	v_mul_f32_e32 v64, v73, v4
	v_fmac_f32_e32 v64, v72, v3
	v_mul_f32_e32 v72, v75, v6
	v_fmac_f32_e32 v72, v74, v5
	v_add_f32_e32 v64, v64, v72
	v_add_f32_e32 v61, v61, v64
	s_waitcnt lgkmcnt(0)
	v_mul_f32_e32 v64, v77, v16
	v_mul_f32_e32 v72, v79, v15
	v_fmac_f32_e32 v64, v76, v14
	v_fmac_f32_e32 v72, v78, v13
	v_add_f32_e32 v64, v64, v72
	ds_read_b128 v[72:75], v63 offset:2752
	ds_read_b128 v[76:79], v63 offset:2768
	v_add_f32_e32 v61, v61, v64
	v_mul_f32_e64 v64, |v61|, s64
	v_exp_f32_e32 v64, v64
	s_waitcnt lgkmcnt(1)
	v_mul_f32_e32 v73, v73, v2
	v_fmac_f32_e32 v73, v72, v17
	v_mul_f32_e32 v72, v75, v12
	v_fmac_f32_e32 v72, v74, v10
	v_add_f32_e32 v72, v73, v72
	s_waitcnt lgkmcnt(0)
	v_mul_f32_e32 v77, v77, v11
	v_add_f32_e32 v80, v18, v72
	v_fmac_f32_e32 v77, v76, v8
	v_mul_f32_e32 v76, v79, v9
	ds_read_b128 v[72:75], v63 offset:2784
	v_fmac_f32_e32 v76, v78, v7
	v_add_f32_e32 v76, v77, v76
	v_add_f32_e32 v80, v80, v76
	ds_read_b128 v[76:79], v63 offset:2800
	s_waitcnt lgkmcnt(1)
	v_mul_f32_e32 v73, v73, v4
	v_fmac_f32_e32 v73, v72, v3
	v_mul_f32_e32 v72, v75, v6
	v_fmac_f32_e32 v72, v74, v5
	v_add_f32_e32 v72, v73, v72
	s_waitcnt lgkmcnt(0)
	v_mul_f32_e32 v73, v77, v16
	v_mul_f32_e32 v74, v79, v15
	v_fmac_f32_e32 v73, v76, v14
	v_fmac_f32_e32 v74, v78, v13
	v_add_f32_e32 v72, v80, v72
	v_add_f32_e32 v73, v73, v74
	v_add_f32_e32 v80, v72, v73
	v_add_f32_e32 v64, 1.0, v64
	v_mul_f32_e64 v72, |v80|, s64
	v_log_f32_e32 v64, v64
	v_exp_f32_e32 v76, v72
	ds_read_b128 v[72:75], v63 offset:2816
	v_min_f32_e32 v61, 0, v61
	v_fmac_f32_e32 v61, 0xbf317218, v64
	v_add_f32_e32 v64, 1.0, v76
	ds_read_b128 v[76:79], v63 offset:2832
	s_waitcnt lgkmcnt(1)
	v_mul_f32_e32 v73, v73, v2
	v_fmac_f32_e32 v73, v72, v17
	v_mul_f32_e32 v72, v75, v12
	v_fmac_f32_e32 v72, v74, v10
	v_add_f32_e32 v72, v73, v72
	s_waitcnt lgkmcnt(0)
	v_mul_f32_e32 v77, v77, v11
	v_add_f32_e32 v81, v18, v72
	v_fmac_f32_e32 v77, v76, v8
	v_mul_f32_e32 v76, v79, v9
	ds_read_b128 v[72:75], v63 offset:2848
	v_fmac_f32_e32 v76, v78, v7
	v_add_f32_e32 v76, v77, v76
	v_add_f32_e32 v81, v81, v76
	ds_read_b128 v[76:79], v63 offset:2864
	s_waitcnt lgkmcnt(1)
	v_mul_f32_e32 v73, v73, v4
	v_fmac_f32_e32 v73, v72, v3
	v_mul_f32_e32 v72, v75, v6
	v_fmac_f32_e32 v72, v74, v5
	v_add_f32_e32 v72, v73, v72
	s_waitcnt lgkmcnt(0)
	v_mul_f32_e32 v73, v77, v16
	v_mul_f32_e32 v74, v79, v15
	v_fmac_f32_e32 v73, v76, v14
	v_fmac_f32_e32 v74, v78, v13
	v_add_f32_e32 v72, v81, v72
	v_add_f32_e32 v73, v73, v74
	v_add_f32_e32 v81, v72, v73
	v_mul_f32_e64 v72, |v81|, s64
	v_log_f32_e32 v64, v64
	v_exp_f32_e32 v76, v72
	ds_read_b128 v[72:75], v63 offset:2880
	v_min_f32_e32 v80, 0, v80
	v_fmac_f32_e32 v80, 0xbf317218, v64
	v_add_f32_e32 v64, 1.0, v76
	ds_read_b128 v[76:79], v63 offset:2896
	v_log_f32_e32 v82, v64
	s_waitcnt lgkmcnt(1)
	v_mul_f32_e32 v64, v73, v2
	v_fmac_f32_e32 v64, v72, v17
	v_mul_f32_e32 v72, v75, v12
	v_fmac_f32_e32 v72, v74, v10
	v_add_f32_e32 v64, v64, v72
	s_waitcnt lgkmcnt(0)
	v_mul_f32_e32 v77, v77, v11
	ds_read_b128 v[72:75], v63 offset:2912
	v_fmac_f32_e32 v77, v76, v8
	v_mul_f32_e32 v76, v79, v9
	v_fmac_f32_e32 v76, v78, v7
	v_add_f32_e32 v64, v18, v64
	v_add_f32_e32 v76, v77, v76
	v_add_f32_e32 v64, v64, v76
	ds_read_b128 v[76:79], v63 offset:2928
	s_waitcnt lgkmcnt(1)
	v_mul_f32_e32 v73, v73, v4
	v_fmac_f32_e32 v73, v72, v3
	v_mul_f32_e32 v72, v75, v6
	v_fmac_f32_e32 v72, v74, v5
	v_add_f32_e32 v72, v73, v72
	v_add_f32_e32 v64, v64, v72
	s_waitcnt lgkmcnt(0)
	v_mul_f32_e32 v72, v77, v16
	v_mul_f32_e32 v73, v79, v15
	v_fmac_f32_e32 v72, v76, v14
	v_fmac_f32_e32 v73, v78, v13
	v_add_f32_e32 v72, v72, v73
	v_add_f32_e32 v73, v64, v72
	v_mul_f32_e64 v64, |v73|, s64
	v_exp_f32_e32 v72, v64
	v_fmamk_f32 v60, v60, 0x3d800000, v59
	ds_read_b128 v[74:77], v63 offset:2944
	v_fmamk_f32 v61, v61, 0x3d800000, v60
	v_add_f32_e32 v72, 1.0, v72
	v_log_f32_e32 v79, v72
	v_min_f32_e32 v78, 0, v81
	v_fmamk_f32 v64, v80, 0x3d800000, v61
	v_fmac_f32_e32 v78, 0xbf317218, v82
	v_min_f32_e32 v73, 0, v73
	v_fmamk_f32 v72, v78, 0x3d800000, v64
	v_fmac_f32_e32 v73, 0xbf317218, v79
	ds_read_b128 v[78:81], v63 offset:2960
	s_waitcnt lgkmcnt(1)
	v_mul_f32_e32 v75, v75, v2
	v_fmac_f32_e32 v75, v74, v17
	v_mul_f32_e32 v74, v77, v12
	v_fmac_f32_e32 v74, v76, v10
	v_add_f32_e32 v74, v75, v74
	s_waitcnt lgkmcnt(0)
	v_mul_f32_e32 v79, v79, v11
	v_add_f32_e32 v82, v18, v74
	v_fmac_f32_e32 v79, v78, v8
	v_mul_f32_e32 v78, v81, v9
	ds_read_b128 v[74:77], v63 offset:2976
	v_fmac_f32_e32 v78, v80, v7
	v_add_f32_e32 v78, v79, v78
	v_add_f32_e32 v82, v82, v78
	ds_read_b128 v[78:81], v63 offset:2992
	s_waitcnt lgkmcnt(1)
	v_mul_f32_e32 v75, v75, v4
	v_fmac_f32_e32 v75, v74, v3
	v_mul_f32_e32 v74, v77, v6
	v_fmac_f32_e32 v74, v76, v5
	v_add_f32_e32 v74, v75, v74
	s_waitcnt lgkmcnt(0)
	v_mul_f32_e32 v75, v79, v16
	v_mul_f32_e32 v76, v81, v15
	v_fmac_f32_e32 v75, v78, v14
	v_fmac_f32_e32 v76, v80, v13
	v_add_f32_e32 v74, v82, v74
	v_add_f32_e32 v75, v75, v76
	v_add_f32_e32 v78, v74, v75
	v_mul_f32_e64 v74, |v78|, s64
	v_exp_f32_e32 v79, v74
	ds_read_b128 v[74:77], v63 offset:3008
	v_min_f32_e32 v82, 0, v78
	v_fmamk_f32 v73, v73, 0x3d800000, v72
	v_add_f32_e32 v78, 1.0, v79
	v_log_f32_e32 v83, v78
	ds_read_b128 v[78:81], v63 offset:3024
	s_waitcnt lgkmcnt(1)
	v_mul_f32_e32 v75, v75, v2
	v_fmac_f32_e32 v75, v74, v17
	v_mul_f32_e32 v74, v77, v12
	v_fmac_f32_e32 v74, v76, v10
	v_add_f32_e32 v74, v75, v74
	s_waitcnt lgkmcnt(0)
	v_mul_f32_e32 v79, v79, v11
	v_add_f32_e32 v115, v18, v74
	v_fmac_f32_e32 v79, v78, v8
	v_mul_f32_e32 v78, v81, v9
	ds_read_b128 v[74:77], v63 offset:3040
	v_fmac_f32_e32 v78, v80, v7
	v_add_f32_e32 v78, v79, v78
	v_add_f32_e32 v115, v115, v78
	ds_read_b128 v[78:81], v63 offset:3056
	s_waitcnt lgkmcnt(1)
	v_mul_f32_e32 v75, v75, v4
	v_fmac_f32_e32 v75, v74, v3
	v_mul_f32_e32 v74, v77, v6
	v_fmac_f32_e32 v74, v76, v5
	v_add_f32_e32 v74, v75, v74
	s_waitcnt lgkmcnt(0)
	v_mul_f32_e32 v75, v79, v16
	v_mul_f32_e32 v76, v81, v15
	v_fmac_f32_e32 v75, v78, v14
	v_fmac_f32_e32 v76, v80, v13
	v_add_f32_e32 v74, v115, v74
	v_add_f32_e32 v75, v75, v76
	v_add_f32_e32 v75, v74, v75
	v_mul_f32_e64 v74, |v75|, s64
	v_exp_f32_e32 v80, v74
	ds_read_b128 v[76:79], v63 offset:3072
	v_fmac_f32_e32 v82, 0xbf317218, v83
	v_fmamk_f32 v74, v82, 0x3d800000, v73
	v_add_f32_e32 v80, 1.0, v80
	v_log_f32_e32 v115, v80
	ds_read_b128 v[80:83], v63 offset:3088
	s_waitcnt lgkmcnt(1)
	v_mul_f32_e32 v77, v77, v2
	v_fmac_f32_e32 v77, v76, v17
	v_mul_f32_e32 v76, v79, v12
	v_fmac_f32_e32 v76, v78, v10
	v_add_f32_e32 v76, v77, v76
	s_waitcnt lgkmcnt(0)
	v_mul_f32_e32 v81, v81, v11
	v_add_f32_e32 v116, v18, v76
	v_fmac_f32_e32 v81, v80, v8
	v_mul_f32_e32 v80, v83, v9
	ds_read_b128 v[76:79], v63 offset:3104
	v_fmac_f32_e32 v80, v82, v7
	v_add_f32_e32 v80, v81, v80
	v_add_f32_e32 v116, v116, v80
	ds_read_b128 v[80:83], v63 offset:3120
	s_waitcnt lgkmcnt(1)
	v_mul_f32_e32 v77, v77, v4
	v_fmac_f32_e32 v77, v76, v3
	v_mul_f32_e32 v76, v79, v6
	v_fmac_f32_e32 v76, v78, v5
	v_add_f32_e32 v76, v77, v76
	s_waitcnt lgkmcnt(0)
	v_mul_f32_e32 v77, v81, v16
	v_mul_f32_e32 v78, v83, v15
	v_fmac_f32_e32 v77, v80, v14
	v_fmac_f32_e32 v78, v82, v13
	v_add_f32_e32 v76, v116, v76
	v_add_f32_e32 v77, v77, v78
	v_add_f32_e32 v116, v76, v77
	v_mul_f32_e64 v76, |v116|, s64
	v_exp_f32_e32 v80, v76
	ds_read_b128 v[76:79], v63 offset:3136
	v_min_f32_e32 v75, 0, v75
	v_fmac_f32_e32 v75, 0xbf317218, v115
	v_add_f32_e32 v80, 1.0, v80
	v_log_f32_e32 v115, v80
	ds_read_b128 v[80:83], v63 offset:3152
	s_waitcnt lgkmcnt(1)
	v_mul_f32_e32 v77, v77, v2
	v_fmac_f32_e32 v77, v76, v17
	v_mul_f32_e32 v76, v79, v12
	v_fmac_f32_e32 v76, v78, v10
	v_add_f32_e32 v76, v77, v76
	s_waitcnt lgkmcnt(0)
	v_mul_f32_e32 v81, v81, v11
	v_add_f32_e32 v117, v18, v76
	v_fmac_f32_e32 v81, v80, v8
	v_mul_f32_e32 v80, v83, v9
	ds_read_b128 v[76:79], v63 offset:3168
	v_fmac_f32_e32 v80, v82, v7
	v_add_f32_e32 v80, v81, v80
	v_add_f32_e32 v117, v117, v80
	ds_read_b128 v[80:83], v63 offset:3184
	s_waitcnt lgkmcnt(1)
	v_mul_f32_e32 v77, v77, v4
	v_fmac_f32_e32 v77, v76, v3
	v_mul_f32_e32 v76, v79, v6
	v_fmac_f32_e32 v76, v78, v5
	v_add_f32_e32 v76, v77, v76
	s_waitcnt lgkmcnt(0)
	v_mul_f32_e32 v77, v81, v16
	v_mul_f32_e32 v78, v83, v15
	v_fmac_f32_e32 v77, v80, v14
	v_fmac_f32_e32 v78, v82, v13
	v_add_f32_e32 v76, v117, v76
	v_add_f32_e32 v77, v77, v78
	v_add_f32_e32 v77, v76, v77
	ds_read_b128 v[78:81], v63 offset:3200
	v_mul_f32_e64 v76, |v77|, s64
	v_exp_f32_e32 v76, v76
	v_min_f32_e32 v82, 0, v116
	ds_read_b128 v[116:119], v63 offset:3216
	s_waitcnt lgkmcnt(1)
	v_mul_f32_e32 v79, v79, v2
	v_add_f32_e32 v76, 1.0, v76
	v_fmac_f32_e32 v79, v78, v17
	v_mul_f32_e32 v78, v81, v12
	v_log_f32_e32 v83, v76
	v_fmac_f32_e32 v78, v80, v10
	v_fmamk_f32 v75, v75, 0x3d800000, v74
	v_fmac_f32_e32 v82, 0xbf317218, v115
	v_add_f32_e32 v78, v79, v78
	v_fmamk_f32 v76, v82, 0x3d800000, v75
	v_add_f32_e32 v82, v18, v78
	ds_read_b128 v[78:81], v63 offset:3232
	v_min_f32_e32 v77, 0, v77
	v_fmac_f32_e32 v77, 0xbf317218, v83
	s_waitcnt lgkmcnt(1)
	v_mul_f32_e32 v83, v117, v11
	v_mul_f32_e32 v115, v119, v9
	v_fmac_f32_e32 v83, v116, v8
	v_fmac_f32_e32 v115, v118, v7
	ds_read_b128 v[116:119], v63 offset:3248
	s_waitcnt lgkmcnt(1)
	v_mul_f32_e32 v79, v79, v4
	v_fmac_f32_e32 v79, v78, v3
	v_mul_f32_e32 v78, v81, v6
	v_fmac_f32_e32 v78, v80, v5
	v_add_f32_e32 v83, v83, v115
	v_add_f32_e32 v78, v79, v78
	s_waitcnt lgkmcnt(0)
	v_mul_f32_e32 v79, v117, v16
	v_mul_f32_e32 v80, v119, v15
	v_add_f32_e32 v82, v82, v83
	v_fmac_f32_e32 v79, v116, v14
	v_fmac_f32_e32 v80, v118, v13
	v_add_f32_e32 v78, v82, v78
	v_add_f32_e32 v79, v79, v80
	v_add_f32_e32 v82, v78, v79
	v_mul_f32_e64 v78, |v82|, s64
	v_exp_f32_e32 v83, v78
	ds_read_b128 v[78:81], v63 offset:3264
	ds_read_b128 v[116:119], v63 offset:3280
	v_min_f32_e32 v115, 0, v82
	v_add_f32_e32 v82, 1.0, v83
	v_log_f32_e32 v82, v82
	s_waitcnt lgkmcnt(1)
	v_mul_f32_e32 v79, v79, v2
	v_fmac_f32_e32 v79, v78, v17
	v_mul_f32_e32 v78, v81, v12
	v_fmac_f32_e32 v78, v80, v10
	v_add_f32_e32 v78, v79, v78
	s_waitcnt lgkmcnt(0)
	v_mul_f32_e32 v117, v117, v11
	v_add_f32_e32 v83, v18, v78
	v_fmac_f32_e32 v117, v116, v8
	v_mul_f32_e32 v116, v119, v9
	ds_read_b128 v[78:81], v63 offset:3296
	v_fmac_f32_e32 v116, v118, v7
	v_add_f32_e32 v116, v117, v116
	v_add_f32_e32 v83, v83, v116
	ds_read_b128 v[116:119], v63 offset:3312
	s_waitcnt lgkmcnt(1)
	v_mul_f32_e32 v79, v79, v4
	v_fmac_f32_e32 v79, v78, v3
	v_mul_f32_e32 v78, v81, v6
	v_fmac_f32_e32 v78, v80, v5
	v_add_f32_e32 v78, v79, v78
	s_waitcnt lgkmcnt(0)
	v_mul_f32_e32 v79, v117, v16
	v_mul_f32_e32 v80, v119, v15
	v_fmac_f32_e32 v79, v116, v14
	v_fmac_f32_e32 v80, v118, v13
	v_add_f32_e32 v78, v83, v78
	v_add_f32_e32 v79, v79, v80
	v_add_f32_e32 v79, v78, v79
	v_mul_f32_e64 v78, |v79|, s64
	v_exp_f32_e32 v116, v78
	v_fmac_f32_e32 v115, 0xbf317218, v82
	ds_read_b128 v[80:83], v63 offset:3328
	v_fmamk_f32 v77, v77, 0x3d800000, v76
	v_fmamk_f32 v78, v115, 0x3d800000, v77
	v_add_f32_e32 v115, 1.0, v116
	ds_read_b128 v[116:119], v63 offset:3344
	s_waitcnt lgkmcnt(1)
	v_mul_f32_e32 v81, v81, v2
	v_fmac_f32_e32 v81, v80, v17
	v_mul_f32_e32 v80, v83, v12
	v_fmac_f32_e32 v80, v82, v10
	v_add_f32_e32 v80, v81, v80
	s_waitcnt lgkmcnt(0)
	v_mul_f32_e32 v117, v117, v11
	v_add_f32_e32 v120, v18, v80
	v_fmac_f32_e32 v117, v116, v8
	v_mul_f32_e32 v116, v119, v9
	ds_read_b128 v[80:83], v63 offset:3360
	v_fmac_f32_e32 v116, v118, v7
	v_add_f32_e32 v116, v117, v116
	v_add_f32_e32 v120, v120, v116
	ds_read_b128 v[116:119], v63 offset:3376
	s_waitcnt lgkmcnt(1)
	v_mul_f32_e32 v81, v81, v4
	v_fmac_f32_e32 v81, v80, v3
	v_mul_f32_e32 v80, v83, v6
	v_fmac_f32_e32 v80, v82, v5
	v_add_f32_e32 v80, v81, v80
	s_waitcnt lgkmcnt(0)
	v_mul_f32_e32 v81, v117, v16
	v_mul_f32_e32 v82, v119, v15
	v_fmac_f32_e32 v81, v116, v14
	v_fmac_f32_e32 v82, v118, v13
	v_add_f32_e32 v80, v120, v80
	v_add_f32_e32 v81, v81, v82
	v_add_f32_e32 v120, v80, v81
	v_mul_f32_e64 v80, |v120|, s64
	v_log_f32_e32 v115, v115
	v_exp_f32_e32 v116, v80
	ds_read_b128 v[80:83], v63 offset:3392
	v_min_f32_e32 v79, 0, v79
	v_fmac_f32_e32 v79, 0xbf317218, v115
	v_add_f32_e32 v115, 1.0, v116
	ds_read_b128 v[116:119], v63 offset:3408
	s_waitcnt lgkmcnt(1)
	v_mul_f32_e32 v81, v81, v2
	v_fmac_f32_e32 v81, v80, v17
	v_mul_f32_e32 v80, v83, v12
	v_fmac_f32_e32 v80, v82, v10
	v_add_f32_e32 v80, v81, v80
	s_waitcnt lgkmcnt(0)
	v_mul_f32_e32 v117, v117, v11
	v_add_f32_e32 v121, v18, v80
	v_fmac_f32_e32 v117, v116, v8
	v_mul_f32_e32 v116, v119, v9
	ds_read_b128 v[80:83], v63 offset:3424
	v_fmac_f32_e32 v116, v118, v7
	v_add_f32_e32 v116, v117, v116
	v_add_f32_e32 v121, v121, v116
	ds_read_b128 v[116:119], v63 offset:3440
	s_waitcnt lgkmcnt(1)
	v_mul_f32_e32 v81, v81, v4
	v_fmac_f32_e32 v81, v80, v3
	v_mul_f32_e32 v80, v83, v6
	v_fmac_f32_e32 v80, v82, v5
	v_add_f32_e32 v80, v81, v80
	s_waitcnt lgkmcnt(0)
	v_mul_f32_e32 v81, v117, v16
	v_mul_f32_e32 v82, v119, v15
	v_fmac_f32_e32 v81, v116, v14
	v_fmac_f32_e32 v82, v118, v13
	v_add_f32_e32 v80, v121, v80
	v_add_f32_e32 v81, v81, v82
	v_add_f32_e32 v81, v80, v81
	v_mul_f32_e64 v80, |v81|, s64
	v_exp_f32_e32 v80, v80
	v_log_f32_e32 v115, v115
	ds_read_b128 v[116:119], v63 offset:3456
	v_min_f32_e32 v82, 0, v120
	v_add_f32_e32 v80, 1.0, v80
	v_log_f32_e32 v83, v80
	ds_read_b128 v[120:123], v63 offset:3472
	v_fmamk_f32 v79, v79, 0x3d800000, v78
	v_fmac_f32_e32 v82, 0xbf317218, v115
	v_min_f32_e32 v81, 0, v81
	v_fmamk_f32 v80, v82, 0x3d800000, v79
	v_fmac_f32_e32 v81, 0xbf317218, v83
	s_waitcnt lgkmcnt(1)
	v_mul_f32_e32 v82, v117, v2
	v_mul_f32_e32 v83, v119, v12
	v_fmac_f32_e32 v82, v116, v17
	v_fmac_f32_e32 v83, v118, v10
	ds_read_b128 v[116:119], v63 offset:3488
	v_add_f32_e32 v82, v82, v83
	s_waitcnt lgkmcnt(1)
	v_mul_f32_e32 v83, v121, v11
	v_mul_f32_e32 v115, v123, v9
	v_fmac_f32_e32 v83, v120, v8
	v_fmac_f32_e32 v115, v122, v7
	ds_read_b128 v[120:123], v63 offset:3504
	v_add_f32_e32 v82, v18, v82
	v_add_f32_e32 v83, v83, v115
	v_add_f32_e32 v82, v82, v83
	s_waitcnt lgkmcnt(1)
	v_mul_f32_e32 v83, v117, v4
	v_mul_f32_e32 v115, v119, v6
	v_fmac_f32_e32 v83, v116, v3
	v_fmac_f32_e32 v115, v118, v5
	ds_read_b128 v[116:119], v63 offset:3520
	v_add_f32_e32 v83, v83, v115
	v_add_f32_e32 v82, v82, v83
	s_waitcnt lgkmcnt(1)
	v_mul_f32_e32 v83, v121, v16
	v_mul_f32_e32 v115, v123, v15
	v_fmac_f32_e32 v83, v120, v14
	v_fmac_f32_e32 v115, v122, v13
	ds_read_b128 v[120:123], v63 offset:3536
	v_add_f32_e32 v83, v83, v115
	s_waitcnt lgkmcnt(1)
	v_mul_f32_e32 v115, v117, v2
	v_fmac_f32_e32 v115, v116, v17
	v_mul_f32_e32 v116, v119, v12
	v_fmac_f32_e32 v116, v118, v10
	v_add_f32_e32 v115, v115, v116
	s_waitcnt lgkmcnt(0)
	v_mul_f32_e32 v121, v121, v11
	ds_read_b128 v[116:119], v63 offset:3552
	v_fmac_f32_e32 v121, v120, v8
	v_mul_f32_e32 v120, v123, v9
	v_fmac_f32_e32 v120, v122, v7
	v_add_f32_e32 v115, v18, v115
	v_add_f32_e32 v120, v121, v120
	v_add_f32_e32 v115, v115, v120
	ds_read_b128 v[120:123], v63 offset:3568
	s_waitcnt lgkmcnt(1)
	v_mul_f32_e32 v117, v117, v4
	v_fmac_f32_e32 v117, v116, v3
	v_mul_f32_e32 v116, v119, v6
	v_add_f32_e32 v82, v82, v83
	v_fmac_f32_e32 v116, v118, v5
	v_mul_f32_e64 v83, |v82|, s64
	v_add_f32_e32 v116, v117, v116
	v_exp_f32_e32 v83, v83
	v_add_f32_e32 v115, v115, v116
	s_waitcnt lgkmcnt(0)
	v_mul_f32_e32 v116, v121, v16
	v_mul_f32_e32 v117, v123, v15
	v_fmac_f32_e32 v116, v120, v14
	v_fmac_f32_e32 v117, v122, v13
	v_add_f32_e32 v116, v116, v117
	v_add_f32_e32 v115, v115, v116
	v_add_f32_e32 v83, 1.0, v83
	v_mul_f32_e64 v116, |v115|, s64
	v_log_f32_e32 v83, v83
	v_exp_f32_e32 v120, v116
	ds_read_b128 v[116:119], v63 offset:3584
	v_min_f32_e32 v82, 0, v82
	v_fmac_f32_e32 v82, 0xbf317218, v83
	v_add_f32_e32 v83, 1.0, v120
	ds_read_b128 v[120:123], v63 offset:3600
	s_waitcnt lgkmcnt(1)
	v_mul_f32_e32 v117, v117, v2
	v_fmac_f32_e32 v117, v116, v17
	v_mul_f32_e32 v116, v119, v12
	v_fmac_f32_e32 v116, v118, v10
	v_add_f32_e32 v116, v117, v116
	s_waitcnt lgkmcnt(0)
	v_mul_f32_e32 v121, v121, v11
	v_add_f32_e32 v124, v18, v116
	v_fmac_f32_e32 v121, v120, v8
	v_mul_f32_e32 v120, v123, v9
	ds_read_b128 v[116:119], v63 offset:3616
	v_fmac_f32_e32 v120, v122, v7
	v_add_f32_e32 v120, v121, v120
	v_add_f32_e32 v124, v124, v120
	ds_read_b128 v[120:123], v63 offset:3632
	s_waitcnt lgkmcnt(1)
	v_mul_f32_e32 v117, v117, v4
	v_fmac_f32_e32 v117, v116, v3
	v_mul_f32_e32 v116, v119, v6
	v_fmac_f32_e32 v116, v118, v5
	v_add_f32_e32 v116, v117, v116
	s_waitcnt lgkmcnt(0)
	v_mul_f32_e32 v117, v121, v16
	v_mul_f32_e32 v118, v123, v15
	v_fmac_f32_e32 v117, v120, v14
	v_fmac_f32_e32 v118, v122, v13
	v_add_f32_e32 v116, v124, v116
	v_add_f32_e32 v117, v117, v118
	v_add_f32_e32 v124, v116, v117
	v_mul_f32_e64 v116, |v124|, s64
	v_log_f32_e32 v83, v83
	v_exp_f32_e32 v120, v116
	ds_read_b128 v[116:119], v63 offset:3648
	v_min_f32_e32 v115, 0, v115
	v_fmac_f32_e32 v115, 0xbf317218, v83
	v_add_f32_e32 v83, 1.0, v120
	ds_read_b128 v[120:123], v63 offset:3664
	v_log_f32_e32 v125, v83
	s_waitcnt lgkmcnt(1)
	v_mul_f32_e32 v83, v117, v2
	v_fmac_f32_e32 v83, v116, v17
	v_mul_f32_e32 v116, v119, v12
	v_fmac_f32_e32 v116, v118, v10
	v_add_f32_e32 v83, v83, v116
	s_waitcnt lgkmcnt(0)
	v_mul_f32_e32 v121, v121, v11
	ds_read_b128 v[116:119], v63 offset:3680
	v_fmac_f32_e32 v121, v120, v8
	v_mul_f32_e32 v120, v123, v9
	v_fmac_f32_e32 v120, v122, v7
	v_add_f32_e32 v83, v18, v83
	v_add_f32_e32 v120, v121, v120
	v_add_f32_e32 v83, v83, v120
	ds_read_b128 v[120:123], v63 offset:3696
	s_waitcnt lgkmcnt(1)
	v_mul_f32_e32 v117, v117, v4
	v_fmac_f32_e32 v117, v116, v3
	v_mul_f32_e32 v116, v119, v6
	v_fmac_f32_e32 v116, v118, v5
	v_add_f32_e32 v116, v117, v116
	v_add_f32_e32 v83, v83, v116
	s_waitcnt lgkmcnt(0)
	v_mul_f32_e32 v116, v121, v16
	v_mul_f32_e32 v117, v123, v15
	v_fmac_f32_e32 v116, v120, v14
	v_fmac_f32_e32 v117, v122, v13
	v_add_f32_e32 v116, v116, v117
	v_add_f32_e32 v120, v83, v116
	v_mul_f32_e64 v83, |v120|, s64
	v_exp_f32_e32 v116, v83
	v_fmamk_f32 v81, v81, 0x3d800000, v80
	v_fmamk_f32 v82, v82, 0x3d800000, v81
	v_fmamk_f32 v83, v115, 0x3d800000, v82
	v_add_f32_e32 v116, 1.0, v116
	v_log_f32_e32 v121, v116
	ds_read_b128 v[116:119], v63 offset:3712
	v_min_f32_e32 v115, 0, v124
	v_min_f32_e32 v124, 0, v120
	v_fmac_f32_e32 v124, 0xbf317218, v121
	ds_read_b128 v[120:123], v63 offset:3728
	s_waitcnt lgkmcnt(1)
	v_mul_f32_e32 v117, v117, v2
	v_fmac_f32_e32 v117, v116, v17
	v_mul_f32_e32 v116, v119, v12
	v_fmac_f32_e32 v116, v118, v10
	v_add_f32_e32 v116, v117, v116
	s_waitcnt lgkmcnt(0)
	v_mul_f32_e32 v121, v121, v11
	v_fmac_f32_e32 v115, 0xbf317218, v125
	v_add_f32_e32 v125, v18, v116
	v_fmac_f32_e32 v121, v120, v8
	v_mul_f32_e32 v120, v123, v9
	ds_read_b128 v[116:119], v63 offset:3744
	v_fmac_f32_e32 v120, v122, v7
	v_add_f32_e32 v120, v121, v120
	v_add_f32_e32 v125, v125, v120
	ds_read_b128 v[120:123], v63 offset:3760
	s_waitcnt lgkmcnt(1)
	v_mul_f32_e32 v117, v117, v4
	v_fmac_f32_e32 v117, v116, v3
	v_mul_f32_e32 v116, v119, v6
	v_fmac_f32_e32 v116, v118, v5
	v_add_f32_e32 v116, v117, v116
	s_waitcnt lgkmcnt(0)
	v_mul_f32_e32 v117, v121, v16
	v_mul_f32_e32 v118, v123, v15
	v_fmac_f32_e32 v117, v120, v14
	v_fmac_f32_e32 v118, v122, v13
	v_add_f32_e32 v116, v125, v116
	v_add_f32_e32 v117, v117, v118
	v_add_f32_e32 v117, v116, v117
	v_mul_f32_e64 v116, |v117|, s64
	v_exp_f32_e32 v122, v116
	ds_read_b128 v[118:121], v63 offset:3776
	v_fmamk_f32 v115, v115, 0x3d800000, v83
	v_fmamk_f32 v116, v124, 0x3d800000, v115
	v_add_f32_e32 v122, 1.0, v122
	v_log_f32_e32 v126, v122
	ds_read_b128 v[122:125], v63 offset:3792
	s_waitcnt lgkmcnt(1)
	v_mul_f32_e32 v119, v119, v2
	v_fmac_f32_e32 v119, v118, v17
	v_mul_f32_e32 v118, v121, v12
	v_fmac_f32_e32 v118, v120, v10
	v_add_f32_e32 v118, v119, v118
	s_waitcnt lgkmcnt(0)
	v_mul_f32_e32 v123, v123, v11
	v_add_f32_e32 v127, v18, v118
	v_fmac_f32_e32 v123, v122, v8
	v_mul_f32_e32 v122, v125, v9
	ds_read_b128 v[118:121], v63 offset:3808
	v_fmac_f32_e32 v122, v124, v7
	v_add_f32_e32 v122, v123, v122
	v_add_f32_e32 v127, v127, v122
	ds_read_b128 v[122:125], v63 offset:3824
	s_waitcnt lgkmcnt(1)
	v_mul_f32_e32 v119, v119, v4
	v_fmac_f32_e32 v119, v118, v3
	v_mul_f32_e32 v118, v121, v6
	v_fmac_f32_e32 v118, v120, v5
	v_add_f32_e32 v118, v119, v118
	s_waitcnt lgkmcnt(0)
	v_mul_f32_e32 v119, v123, v16
	v_mul_f32_e32 v120, v125, v15
	v_fmac_f32_e32 v119, v122, v14
	v_fmac_f32_e32 v120, v124, v13
	v_add_f32_e32 v118, v127, v118
	v_add_f32_e32 v119, v119, v120
	v_add_f32_e32 v127, v118, v119
	v_mul_f32_e64 v118, |v127|, s64
	v_exp_f32_e32 v122, v118
	ds_read_b128 v[118:121], v63 offset:3840
	v_min_f32_e32 v117, 0, v117
	v_fmac_f32_e32 v117, 0xbf317218, v126
	v_add_f32_e32 v122, 1.0, v122
	v_log_f32_e32 v126, v122
	ds_read_b128 v[122:125], v63 offset:3856
	s_waitcnt lgkmcnt(1)
	v_mul_f32_e32 v119, v119, v2
	v_fmac_f32_e32 v119, v118, v17
	v_mul_f32_e32 v118, v121, v12
	v_fmac_f32_e32 v118, v120, v10
	v_add_f32_e32 v118, v119, v118
	s_waitcnt lgkmcnt(0)
	v_mul_f32_e32 v123, v123, v11
	v_add_f32_e32 v128, v18, v118
	v_fmac_f32_e32 v123, v122, v8
	v_mul_f32_e32 v122, v125, v9
	ds_read_b128 v[118:121], v63 offset:3872
	v_fmac_f32_e32 v122, v124, v7
	v_add_f32_e32 v122, v123, v122
	v_add_f32_e32 v128, v128, v122
	ds_read_b128 v[122:125], v63 offset:3888
	s_waitcnt lgkmcnt(1)
	v_mul_f32_e32 v119, v119, v4
	v_fmac_f32_e32 v119, v118, v3
	v_mul_f32_e32 v118, v121, v6
	v_fmac_f32_e32 v118, v120, v5
	v_add_f32_e32 v118, v119, v118
	s_waitcnt lgkmcnt(0)
	v_mul_f32_e32 v119, v123, v16
	v_mul_f32_e32 v120, v125, v15
	v_fmac_f32_e32 v119, v122, v14
	v_fmac_f32_e32 v120, v124, v13
	v_add_f32_e32 v118, v128, v118
	v_add_f32_e32 v119, v119, v120
	v_add_f32_e32 v128, v118, v119
	v_mul_f32_e64 v118, |v128|, s64
	v_exp_f32_e32 v122, v118
	ds_read_b128 v[118:121], v63 offset:3904
	v_min_f32_e32 v127, 0, v127
	v_fmac_f32_e32 v127, 0xbf317218, v126
	v_add_f32_e32 v122, 1.0, v122
	v_log_f32_e32 v126, v122
	ds_read_b128 v[122:125], v63 offset:3920
	s_waitcnt lgkmcnt(1)
	v_mul_f32_e32 v119, v119, v2
	v_fmac_f32_e32 v119, v118, v17
	v_mul_f32_e32 v118, v121, v12
	v_fmac_f32_e32 v118, v120, v10
	v_add_f32_e32 v118, v119, v118
	s_waitcnt lgkmcnt(0)
	v_mul_f32_e32 v123, v123, v11
	v_add_f32_e32 v129, v18, v118
	v_fmac_f32_e32 v123, v122, v8
	v_mul_f32_e32 v122, v125, v9
	ds_read_b128 v[118:121], v63 offset:3936
	v_fmac_f32_e32 v122, v124, v7
	v_add_f32_e32 v122, v123, v122
	v_add_f32_e32 v129, v129, v122
	ds_read_b128 v[122:125], v63 offset:3952
	s_waitcnt lgkmcnt(1)
	v_mul_f32_e32 v119, v119, v4
	v_fmac_f32_e32 v119, v118, v3
	v_mul_f32_e32 v118, v121, v6
	v_fmac_f32_e32 v118, v120, v5
	v_add_f32_e32 v118, v119, v118
	s_waitcnt lgkmcnt(0)
	v_mul_f32_e32 v119, v123, v16
	v_mul_f32_e32 v120, v125, v15
	v_fmac_f32_e32 v119, v122, v14
	v_fmac_f32_e32 v120, v124, v13
	v_add_f32_e32 v118, v129, v118
	v_add_f32_e32 v119, v119, v120
	v_add_f32_e32 v122, v118, v119
	v_mul_f32_e64 v118, |v122|, s64
	v_exp_f32_e32 v118, v118
	v_fmamk_f32 v117, v117, 0x3d800000, v116
	v_min_f32_e32 v119, 0, v128
	v_fmamk_f32 v127, v127, 0x3d800000, v117
	v_add_f32_e32 v118, 1.0, v118
	v_fmac_f32_e32 v119, 0xbf317218, v126
	v_log_f32_e32 v123, v118
	v_fmamk_f32 v126, v119, 0x3d800000, v127
	ds_read_b128 v[118:121], v63 offset:3968
	v_min_f32_e32 v122, 0, v122
	v_fmac_f32_e32 v122, 0xbf317218, v123
	v_fmamk_f32 v128, v122, 0x3d800000, v126
	ds_read_b128 v[122:125], v63 offset:3984
	s_waitcnt lgkmcnt(1)
	v_mul_f32_e32 v119, v119, v2
	v_fmac_f32_e32 v119, v118, v17
	v_mul_f32_e32 v118, v121, v12
	v_fmac_f32_e32 v118, v120, v10
	v_add_f32_e32 v118, v119, v118
	v_add_f32_e32 v129, v18, v118
	s_waitcnt lgkmcnt(0)
	v_mul_f32_e32 v123, v123, v11
	ds_read_b128 v[118:121], v63 offset:4000
	v_fmac_f32_e32 v123, v122, v8
	v_mul_f32_e32 v122, v125, v9
	v_fmac_f32_e32 v122, v124, v7
	v_add_f32_e32 v122, v123, v122
	v_add_f32_e32 v129, v129, v122
	ds_read_b128 v[122:125], v63 offset:4016
	s_waitcnt lgkmcnt(1)
	v_mul_f32_e32 v119, v119, v4
	v_fmac_f32_e32 v119, v118, v3
	v_mul_f32_e32 v118, v121, v6
	v_fmac_f32_e32 v118, v120, v5
	v_add_f32_e32 v118, v119, v118
	v_add_f32_e32 v129, v129, v118
	s_waitcnt lgkmcnt(0)
	v_mul_f32_e32 v118, v123, v16
	v_mul_f32_e32 v119, v125, v15
	v_fmac_f32_e32 v118, v122, v14
	v_fmac_f32_e32 v119, v124, v13
	v_add_f32_e32 v122, v118, v119
	ds_read_b128 v[118:121], v63 offset:4032
	v_add_f32_e32 v129, v129, v122
	v_mul_f32_e64 v122, |v129|, s64
	v_exp_f32_e32 v130, v122
	ds_read_b128 v[122:125], v63 offset:4048
	s_waitcnt lgkmcnt(1)
	v_mul_f32_e32 v2, v119, v2
	v_mul_f32_e32 v12, v121, v12
	v_fmac_f32_e32 v2, v118, v17
	v_fmac_f32_e32 v12, v120, v10
	v_add_f32_e32 v2, v2, v12
	s_waitcnt lgkmcnt(0)
	v_mul_f32_e32 v12, v123, v11
	v_fmac_f32_e32 v12, v122, v8
	v_mul_f32_e32 v17, v125, v9
	ds_read_b128 v[8:11], v63 offset:4064
	ds_read_b128 v[118:121], v63 offset:4080
	v_fmac_f32_e32 v17, v124, v7
	v_add_f32_e32 v2, v18, v2
	v_add_f32_e32 v7, v12, v17
	s_waitcnt lgkmcnt(1)
	v_mul_f32_e32 v4, v9, v4
	v_fmac_f32_e32 v4, v8, v3
	v_mul_f32_e32 v3, v11, v6
	v_fmac_f32_e32 v3, v10, v5
	v_add_f32_e32 v2, v2, v7
	v_add_f32_e32 v3, v4, v3
	v_add_f32_e32 v2, v2, v3
	s_waitcnt lgkmcnt(0)
	v_mul_f32_e32 v3, v119, v16
	v_mul_f32_e32 v4, v121, v15
	v_fmac_f32_e32 v3, v118, v14
	v_fmac_f32_e32 v4, v120, v13
	v_add_f32_e32 v3, v3, v4
	v_add_f32_e32 v2, v2, v3
	v_mul_f32_e64 v3, |v2|, s64
	v_exp_f32_e32 v3, v3
	v_add_f32_e32 v4, 1.0, v130
	v_log_f32_e32 v4, v4
	v_min_f32_e32 v5, 0, v129
	v_add_f32_e32 v3, 1.0, v3
	v_log_f32_e32 v3, v3
	v_fmac_f32_e32 v5, 0xbf317218, v4
	v_min_f32_e32 v2, 0, v2
	v_fmamk_f32 v118, v5, 0x3d800000, v128
	v_fmac_f32_e32 v2, 0xbf317218, v3
	v_fmamk_f32 v119, v2, 0x3d800000, v118
	ds_write_b32 v87, v119 offset:16384
	s_waitcnt lgkmcnt(0)
	s_barrier
	ds_read2st64_b32 v[2:3], v85 offset0:64 offset1:66
	ds_read2st64_b32 v[4:5], v85 offset0:68 offset1:70
	s_waitcnt lgkmcnt(1)
	v_add_f32_e32 v2, 0, v2
	v_cndmask_b32_e64 v6, v2, 0, s[24:25]
	v_add_f32_e32 v7, v6, v3
	v_cndmask_b32_e64 v6, v6, v7, s[4:5]
	s_waitcnt lgkmcnt(0)
	v_add_f32_e32 v7, v6, v4
	v_cndmask_b32_e64 v6, v6, v7, s[6:7]
	v_add_f32_e32 v7, v6, v5
	v_cndmask_b32_e64 v120, v6, v7, s[8:9]
	v_add_f32_e32 v82, v120, v82
	v_add_f32_e32 v167, v120, v64
	v_mul_f32_e32 v64, 0xbfb8aa3b, v82
	v_min_f32_e32 v64, 0x42e60000, v64
	v_add_f32_e32 v83, v120, v83
	v_add_f32_e32 v168, v120, v72
	v_exp_f32_e32 v72, v64
	v_mul_f32_e32 v64, 0xbfb8aa3b, v83
	v_min_f32_e32 v64, 0x42e60000, v64
	v_add_f32_e32 v178, v120, v115
	v_add_f32_e32 v169, v120, v73
	v_exp_f32_e32 v73, v64
	v_mul_f32_e32 v64, 0xbfb8aa3b, v178
	v_min_f32_e32 v64, 0x42e60000, v64
	v_add_f32_e32 v179, v120, v116
	v_add_f32_e32 v170, v120, v74
	v_exp_f32_e32 v74, v64
	v_mul_f32_e32 v64, 0xbfb8aa3b, v179
	v_min_f32_e32 v64, 0x42e60000, v64
	v_add_f32_e32 v180, v120, v117
	v_add_f32_e32 v171, v120, v75
	v_exp_f32_e32 v75, v64
	v_mul_f32_e32 v64, 0xbfb8aa3b, v180
	v_min_f32_e32 v64, 0x42e60000, v64
	v_add_f32_e32 v181, v120, v127
	v_add_f32_e32 v172, v120, v76
	v_exp_f32_e32 v76, v64
	v_mul_f32_e32 v64, 0xbfb8aa3b, v181
	v_mul_f32_e32 v82, 0x3fb8aa3b, v82
	v_mul_f32_e32 v83, 0x3fb8aa3b, v83
	v_min_f32_e32 v64, 0x42e60000, v64
	v_add_f32_e32 v182, v120, v126
	v_exp_f32_e32 v82, v82
	v_exp_f32_e32 v83, v83
	v_add_f32_e32 v173, v120, v77
	v_exp_f32_e32 v77, v64
	v_mul_f32_e32 v64, 0xbfb8aa3b, v182
	v_min_f32_e32 v64, 0x42e60000, v64
	v_add_f32_e32 v183, v120, v128
	v_add_f32_e32 v129, v120, v24
	v_add_f32_e32 v138, v120, v33
	v_add_f32_e32 v139, v120, v34
	v_add_f32_e32 v148, v120, v43
	v_add_f32_e32 v149, v120, v44
	v_add_f32_e32 v158, v120, v53
	v_add_f32_e32 v159, v120, v54
	v_add_f32_e32 v174, v120, v78
	v_exp_f32_e32 v78, v64
	v_mul_f32_e32 v64, 0xbfb8aa3b, v183
	v_add_f32_e32 v124, v120, v22
	v_add_f32_e32 v125, v120, v23
	v_mul_f32_e32 v13, 0xbfb8aa3b, v129
	v_add_f32_e32 v137, v120, v32
	v_mul_f32_e32 v22, 0xbfb8aa3b, v138
	v_mul_f32_e32 v23, 0xbfb8aa3b, v139
	v_add_f32_e32 v147, v120, v42
	v_mul_f32_e32 v32, 0xbfb8aa3b, v148
	v_mul_f32_e32 v33, 0xbfb8aa3b, v149
	v_add_f32_e32 v157, v120, v52
	v_mul_f32_e32 v42, 0xbfb8aa3b, v158
	v_mul_f32_e32 v43, 0xbfb8aa3b, v159
	v_mul_f32_e32 v52, 0xbfb8aa3b, v168
	v_mul_f32_e32 v53, 0xbfb8aa3b, v169
	v_min_f32_e32 v64, 0x42e60000, v64
	v_add_f32_e32 v184, v120, v118
	v_add_f32_e32 v185, v120, v119
	v_mul_f32_e32 v119, 0x3fb8aa3b, v129
	v_mul_f32_e32 v128, 0x3fb8aa3b, v138
	v_mul_f32_e32 v129, 0x3fb8aa3b, v139
	v_mul_f32_e32 v138, 0x3fb8aa3b, v148
	v_mul_f32_e32 v139, 0x3fb8aa3b, v149
	v_mul_f32_e32 v148, 0x3fb8aa3b, v158
	v_mul_f32_e32 v149, 0x3fb8aa3b, v159
	v_mul_f32_e32 v158, 0x3fb8aa3b, v168
	v_mul_f32_e32 v159, 0x3fb8aa3b, v169
	v_mul_f32_e32 v168, 0x3db504f3, v82
	v_mul_f32_e32 v169, 0x3db504f3, v83
	v_mul_f32_e32 v82, 0x3fb8aa3b, v178
	v_mul_f32_e32 v83, 0x3fb8aa3b, v179
	v_add_f32_e32 v175, v120, v79
	v_exp_f32_e32 v79, v64
	v_mul_f32_e32 v64, 0xbfb8aa3b, v184
	v_exp_f32_e32 v82, v82
	v_exp_f32_e32 v83, v83
	v_add_f32_e32 v130, v120, v25
	v_add_f32_e32 v140, v120, v35
	v_add_f32_e32 v150, v120, v45
	v_add_f32_e32 v160, v120, v55
	v_min_f32_e32 v64, 0x42e60000, v64
	v_add_f32_e32 v121, v120, v19
	v_add_f32_e32 v122, v120, v20
	v_add_f32_e32 v123, v120, v21
	v_mul_f32_e32 v14, 0xbfb8aa3b, v130
	v_add_f32_e32 v131, v120, v26
	v_add_f32_e32 v132, v120, v27
	v_add_f32_e32 v133, v120, v28
	v_add_f32_e32 v134, v120, v29
	v_add_f32_e32 v135, v120, v30
	v_add_f32_e32 v136, v120, v31
	v_mul_f32_e32 v24, 0xbfb8aa3b, v140
	v_add_f32_e32 v141, v120, v36
	v_add_f32_e32 v142, v120, v37
	v_add_f32_e32 v143, v120, v38
	v_add_f32_e32 v144, v120, v39
	v_add_f32_e32 v145, v120, v40
	v_add_f32_e32 v146, v120, v41
	v_mul_f32_e32 v34, 0xbfb8aa3b, v150
	v_add_f32_e32 v151, v120, v46
	v_add_f32_e32 v152, v120, v47
	v_add_f32_e32 v153, v120, v48
	v_add_f32_e32 v154, v120, v49
	v_add_f32_e32 v155, v120, v50
	v_add_f32_e32 v156, v120, v51
	v_mul_f32_e32 v44, 0xbfb8aa3b, v160
	v_add_f32_e32 v161, v120, v56
	v_add_f32_e32 v162, v120, v57
	v_add_f32_e32 v163, v120, v58
	v_add_f32_e32 v164, v120, v59
	v_add_f32_e32 v165, v120, v60
	v_add_f32_e32 v166, v120, v61
	v_mul_f32_e32 v54, 0xbfb8aa3b, v170
	v_add_f32_e32 v176, v120, v80
	v_add_f32_e32 v177, v120, v81
	v_exp_f32_e32 v80, v64
	v_mul_f32_e32 v64, 0xbfb8aa3b, v185
	v_mul_f32_e32 v120, 0x3fb8aa3b, v130
	v_mul_f32_e32 v130, 0x3fb8aa3b, v140
	v_mul_f32_e32 v140, 0x3fb8aa3b, v150
	v_mul_f32_e32 v150, 0x3fb8aa3b, v160
	v_mul_f32_e32 v160, 0x3fb8aa3b, v170
	v_mul_f32_e32 v170, 0x3fb8aa3b, v180
	v_mul_f32_e32 v9, 0xbfb8aa3b, v122
	v_mul_f32_e32 v11, 0xbfb8aa3b, v124
	v_mul_f32_e32 v16, 0xbfb8aa3b, v132
	v_mul_f32_e32 v18, 0xbfb8aa3b, v134
	v_mul_f32_e32 v26, 0xbfb8aa3b, v142
	v_mul_f32_e32 v28, 0xbfb8aa3b, v144
	v_mul_f32_e32 v36, 0xbfb8aa3b, v152
	v_mul_f32_e32 v38, 0xbfb8aa3b, v154
	v_mul_f32_e32 v46, 0xbfb8aa3b, v162
	v_mul_f32_e32 v48, 0xbfb8aa3b, v164
	v_mul_f32_e32 v56, 0xbfb8aa3b, v172
	v_mul_f32_e32 v58, 0xbfb8aa3b, v174
	v_min_f32_e32 v64, 0x42e60000, v64
	v_mul_f32_e32 v115, 0x3fb8aa3b, v122
	v_mul_f32_e32 v117, 0x3fb8aa3b, v124
	v_mul_f32_e32 v122, 0x3fb8aa3b, v132
	v_mul_f32_e32 v124, 0x3fb8aa3b, v134
	v_mul_f32_e32 v132, 0x3fb8aa3b, v142
	v_mul_f32_e32 v134, 0x3fb8aa3b, v144
	v_mul_f32_e32 v142, 0x3fb8aa3b, v152
	v_mul_f32_e32 v144, 0x3fb8aa3b, v154
	v_mul_f32_e32 v152, 0x3fb8aa3b, v162
	v_mul_f32_e32 v154, 0x3fb8aa3b, v164
	v_mul_f32_e32 v162, 0x3fb8aa3b, v172
	v_mul_f32_e32 v164, 0x3fb8aa3b, v174
	v_exp_f32_e32 v172, v170
	v_mul_f32_e32 v170, 0x3fb8aa3b, v181
	v_mul_f32_e32 v174, 0x3fb8aa3b, v184
	v_mul_f32_e32 v8, 0xbfb8aa3b, v121
	v_mul_f32_e32 v10, 0xbfb8aa3b, v123
	v_mul_f32_e32 v12, 0xbfb8aa3b, v125
	v_mul_f32_e32 v15, 0xbfb8aa3b, v131
	v_mul_f32_e32 v17, 0xbfb8aa3b, v133
	v_mul_f32_e32 v19, 0xbfb8aa3b, v135
	v_mul_f32_e32 v20, 0xbfb8aa3b, v136
	v_mul_f32_e32 v21, 0xbfb8aa3b, v137
	v_mul_f32_e32 v25, 0xbfb8aa3b, v141
	v_mul_f32_e32 v27, 0xbfb8aa3b, v143
	v_mul_f32_e32 v29, 0xbfb8aa3b, v145
	v_mul_f32_e32 v30, 0xbfb8aa3b, v146
	v_mul_f32_e32 v31, 0xbfb8aa3b, v147
	v_mul_f32_e32 v35, 0xbfb8aa3b, v151
	v_mul_f32_e32 v37, 0xbfb8aa3b, v153
	v_mul_f32_e32 v39, 0xbfb8aa3b, v155
	v_mul_f32_e32 v40, 0xbfb8aa3b, v156
	v_mul_f32_e32 v41, 0xbfb8aa3b, v157
	v_mul_f32_e32 v45, 0xbfb8aa3b, v161
	v_mul_f32_e32 v47, 0xbfb8aa3b, v163
	v_mul_f32_e32 v49, 0xbfb8aa3b, v165
	v_mul_f32_e32 v50, 0xbfb8aa3b, v166
	v_mul_f32_e32 v51, 0xbfb8aa3b, v167
	v_mul_f32_e32 v55, 0xbfb8aa3b, v171
	v_mul_f32_e32 v57, 0xbfb8aa3b, v173
	v_mul_f32_e32 v59, 0xbfb8aa3b, v175
	v_mul_f32_e32 v60, 0xbfb8aa3b, v176
	v_mul_f32_e32 v61, 0xbfb8aa3b, v177
	v_exp_f32_e32 v81, v64
	v_mul_f32_e32 v64, 0x3fb8aa3b, v121
	v_mul_f32_e32 v116, 0x3fb8aa3b, v123
	v_mul_f32_e32 v118, 0x3fb8aa3b, v125
	v_mul_f32_e32 v121, 0x3fb8aa3b, v131
	v_mul_f32_e32 v123, 0x3fb8aa3b, v133
	v_mul_f32_e32 v125, 0x3fb8aa3b, v135
	v_mul_f32_e32 v126, 0x3fb8aa3b, v136
	v_mul_f32_e32 v127, 0x3fb8aa3b, v137
	v_mul_f32_e32 v131, 0x3fb8aa3b, v141
	v_mul_f32_e32 v133, 0x3fb8aa3b, v143
	v_mul_f32_e32 v135, 0x3fb8aa3b, v145
	v_mul_f32_e32 v136, 0x3fb8aa3b, v146
	v_mul_f32_e32 v137, 0x3fb8aa3b, v147
	v_mul_f32_e32 v141, 0x3fb8aa3b, v151
	v_mul_f32_e32 v143, 0x3fb8aa3b, v153
	v_mul_f32_e32 v145, 0x3fb8aa3b, v155
	v_mul_f32_e32 v146, 0x3fb8aa3b, v156
	v_mul_f32_e32 v147, 0x3fb8aa3b, v157
	v_mul_f32_e32 v151, 0x3fb8aa3b, v161
	v_mul_f32_e32 v153, 0x3fb8aa3b, v163
	v_mul_f32_e32 v155, 0x3fb8aa3b, v165
	v_mul_f32_e32 v156, 0x3fb8aa3b, v166
	v_mul_f32_e32 v157, 0x3fb8aa3b, v167
	v_mul_f32_e32 v161, 0x3fb8aa3b, v171
	v_mul_f32_e32 v163, 0x3fb8aa3b, v173
	v_mul_f32_e32 v165, 0x3fb8aa3b, v175
	v_mul_f32_e32 v166, 0x3fb8aa3b, v176
	v_mul_f32_e32 v167, 0x3fb8aa3b, v177
	v_exp_f32_e32 v173, v170
	v_mul_f32_e32 v170, 0x3db504f3, v82
	v_mul_f32_e32 v171, 0x3db504f3, v83
	v_mul_f32_e32 v82, 0x3fb8aa3b, v182
	v_mul_f32_e32 v83, 0x3fb8aa3b, v183
	v_exp_f32_e32 v176, v174
	v_mul_f32_e32 v174, 0x3fb8aa3b, v185
	v_min_f32_e32 v8, 0x42e60000, v8
	v_min_f32_e32 v9, 0x42e60000, v9
	v_min_f32_e32 v10, 0x42e60000, v10
	v_min_f32_e32 v11, 0x42e60000, v11
	v_min_f32_e32 v12, 0x42e60000, v12
	v_min_f32_e32 v13, 0x42e60000, v13
	v_min_f32_e32 v14, 0x42e60000, v14
	v_min_f32_e32 v15, 0x42e60000, v15
	v_min_f32_e32 v16, 0x42e60000, v16
	v_min_f32_e32 v17, 0x42e60000, v17
	v_min_f32_e32 v18, 0x42e60000, v18
	v_min_f32_e32 v19, 0x42e60000, v19
	v_min_f32_e32 v20, 0x42e60000, v20
	v_min_f32_e32 v21, 0x42e60000, v21
	v_min_f32_e32 v22, 0x42e60000, v22
	v_min_f32_e32 v23, 0x42e60000, v23
	v_min_f32_e32 v24, 0x42e60000, v24
	v_min_f32_e32 v25, 0x42e60000, v25
	v_min_f32_e32 v26, 0x42e60000, v26
	v_min_f32_e32 v27, 0x42e60000, v27
	v_min_f32_e32 v28, 0x42e60000, v28
	v_min_f32_e32 v29, 0x42e60000, v29
	v_min_f32_e32 v30, 0x42e60000, v30
	v_min_f32_e32 v31, 0x42e60000, v31
	v_min_f32_e32 v32, 0x42e60000, v32
	v_min_f32_e32 v33, 0x42e60000, v33
	v_min_f32_e32 v34, 0x42e60000, v34
	v_min_f32_e32 v35, 0x42e60000, v35
	v_min_f32_e32 v36, 0x42e60000, v36
	v_min_f32_e32 v37, 0x42e60000, v37
	v_min_f32_e32 v38, 0x42e60000, v38
	v_min_f32_e32 v39, 0x42e60000, v39
	v_min_f32_e32 v40, 0x42e60000, v40
	v_min_f32_e32 v41, 0x42e60000, v41
	v_min_f32_e32 v42, 0x42e60000, v42
	v_min_f32_e32 v43, 0x42e60000, v43
	v_min_f32_e32 v44, 0x42e60000, v44
	v_min_f32_e32 v45, 0x42e60000, v45
	v_min_f32_e32 v46, 0x42e60000, v46
	v_min_f32_e32 v47, 0x42e60000, v47
	v_min_f32_e32 v48, 0x42e60000, v48
	v_min_f32_e32 v49, 0x42e60000, v49
	v_min_f32_e32 v50, 0x42e60000, v50
	v_min_f32_e32 v51, 0x42e60000, v51
	v_min_f32_e32 v52, 0x42e60000, v52
	v_min_f32_e32 v53, 0x42e60000, v53
	v_min_f32_e32 v54, 0x42e60000, v54
	v_min_f32_e32 v55, 0x42e60000, v55
	v_min_f32_e32 v56, 0x42e60000, v56
	v_min_f32_e32 v57, 0x42e60000, v57
	v_min_f32_e32 v58, 0x42e60000, v58
	v_min_f32_e32 v59, 0x42e60000, v59
	v_min_f32_e32 v60, 0x42e60000, v60
	v_min_f32_e32 v61, 0x42e60000, v61
	v_exp_f32_e32 v64, v64
	v_exp_f32_e32 v115, v115
	v_exp_f32_e32 v116, v116
	v_exp_f32_e32 v117, v117
	v_exp_f32_e32 v118, v118
	v_exp_f32_e32 v119, v119
	v_exp_f32_e32 v120, v120
	v_exp_f32_e32 v121, v121
	v_exp_f32_e32 v122, v122
	v_exp_f32_e32 v123, v123
	v_exp_f32_e32 v124, v124
	v_exp_f32_e32 v125, v125
	v_exp_f32_e32 v126, v126
	v_exp_f32_e32 v127, v127
	v_exp_f32_e32 v128, v128
	v_exp_f32_e32 v129, v129
	v_exp_f32_e32 v130, v130
	v_exp_f32_e32 v131, v131
	v_exp_f32_e32 v132, v132
	v_exp_f32_e32 v133, v133
	v_exp_f32_e32 v134, v134
	v_exp_f32_e32 v135, v135
	v_exp_f32_e32 v136, v136
	v_exp_f32_e32 v137, v137
	v_exp_f32_e32 v138, v138
	v_exp_f32_e32 v139, v139
	v_exp_f32_e32 v140, v140
	v_exp_f32_e32 v141, v141
	v_exp_f32_e32 v142, v142
	v_exp_f32_e32 v143, v143
	v_exp_f32_e32 v144, v144
	v_exp_f32_e32 v145, v145
	v_exp_f32_e32 v146, v146
	v_exp_f32_e32 v147, v147
	v_exp_f32_e32 v148, v148
	v_exp_f32_e32 v149, v149
	v_exp_f32_e32 v150, v150
	v_exp_f32_e32 v151, v151
	v_exp_f32_e32 v152, v152
	v_exp_f32_e32 v153, v153
	v_exp_f32_e32 v154, v154
	v_exp_f32_e32 v155, v155
	v_exp_f32_e32 v156, v156
	v_exp_f32_e32 v157, v157
	v_exp_f32_e32 v158, v158
	v_exp_f32_e32 v159, v159
	v_exp_f32_e32 v160, v160
	v_exp_f32_e32 v161, v161
	v_exp_f32_e32 v162, v162
	v_exp_f32_e32 v163, v163
	v_exp_f32_e32 v164, v164
	v_exp_f32_e32 v165, v165
	v_exp_f32_e32 v166, v166
	v_exp_f32_e32 v167, v167
	v_exp_f32_e32 v82, v82
	v_exp_f32_e32 v83, v83
	v_exp_f32_e32 v177, v174
	v_lshl_add_u32 v6, s46, 8, v88
	v_exp_f32_e32 v8, v8
	v_exp_f32_e32 v9, v9
	v_exp_f32_e32 v10, v10
	v_exp_f32_e32 v11, v11
	v_exp_f32_e32 v12, v12
	v_exp_f32_e32 v13, v13
	v_exp_f32_e32 v14, v14
	v_exp_f32_e32 v15, v15
	v_exp_f32_e32 v16, v16
	v_exp_f32_e32 v17, v17
	v_exp_f32_e32 v18, v18
	v_exp_f32_e32 v19, v19
	v_exp_f32_e32 v20, v20
	v_exp_f32_e32 v21, v21
	v_exp_f32_e32 v22, v22
	v_exp_f32_e32 v23, v23
	v_exp_f32_e32 v24, v24
	v_exp_f32_e32 v25, v25
	v_exp_f32_e32 v26, v26
	v_exp_f32_e32 v27, v27
	v_exp_f32_e32 v28, v28
	v_exp_f32_e32 v29, v29
	v_exp_f32_e32 v30, v30
	v_exp_f32_e32 v31, v31
	v_exp_f32_e32 v32, v32
	v_exp_f32_e32 v33, v33
	v_exp_f32_e32 v34, v34
	v_exp_f32_e32 v35, v35
	v_exp_f32_e32 v36, v36
	v_exp_f32_e32 v37, v37
	v_exp_f32_e32 v38, v38
	v_exp_f32_e32 v39, v39
	v_exp_f32_e32 v40, v40
	v_exp_f32_e32 v41, v41
	v_exp_f32_e32 v42, v42
	v_exp_f32_e32 v43, v43
	v_exp_f32_e32 v44, v44
	v_exp_f32_e32 v45, v45
	v_exp_f32_e32 v46, v46
	v_exp_f32_e32 v47, v47
	v_exp_f32_e32 v48, v48
	v_exp_f32_e32 v49, v49
	v_exp_f32_e32 v50, v50
	v_exp_f32_e32 v51, v51
	v_exp_f32_e32 v52, v52
	v_exp_f32_e32 v53, v53
	v_exp_f32_e32 v54, v54
	v_exp_f32_e32 v55, v55
	v_exp_f32_e32 v56, v56
	v_exp_f32_e32 v57, v57
	v_exp_f32_e32 v58, v58
	v_exp_f32_e32 v59, v59
	v_exp_f32_e32 v60, v60
	v_exp_f32_e32 v61, v61
	v_mad_i64_i32 v[6:7], s[48:49], v6, s66, v[68:69]
	v_lshl_add_u64 v[6:7], v[6:7], 0, s[0:1]
	v_lshl_add_u64 v[6:7], v[6:7], 0, v[70:71]
	v_mul_f32_e32 v64, 0x3db504f3, v64
	v_mul_f32_e32 v115, 0x3db504f3, v115
	v_mul_f32_e32 v116, 0x3db504f3, v116
	v_mul_f32_e32 v117, 0x3db504f3, v117
	v_mul_f32_e32 v118, 0x3db504f3, v118
	v_mul_f32_e32 v119, 0x3db504f3, v119
	v_mul_f32_e32 v120, 0x3db504f3, v120
	v_mul_f32_e32 v121, 0x3db504f3, v121
	v_mul_f32_e32 v122, 0x3db504f3, v122
	v_mul_f32_e32 v123, 0x3db504f3, v123
	v_mul_f32_e32 v124, 0x3db504f3, v124
	v_mul_f32_e32 v125, 0x3db504f3, v125
	v_mul_f32_e32 v126, 0x3db504f3, v126
	v_mul_f32_e32 v127, 0x3db504f3, v127
	v_mul_f32_e32 v128, 0x3db504f3, v128
	v_mul_f32_e32 v129, 0x3db504f3, v129
	v_mul_f32_e32 v130, 0x3db504f3, v130
	v_mul_f32_e32 v131, 0x3db504f3, v131
	v_mul_f32_e32 v132, 0x3db504f3, v132
	v_mul_f32_e32 v133, 0x3db504f3, v133
	v_mul_f32_e32 v134, 0x3db504f3, v134
	v_mul_f32_e32 v135, 0x3db504f3, v135
	v_mul_f32_e32 v136, 0x3db504f3, v136
	v_mul_f32_e32 v137, 0x3db504f3, v137
	v_mul_f32_e32 v138, 0x3db504f3, v138
	v_mul_f32_e32 v139, 0x3db504f3, v139
	v_mul_f32_e32 v140, 0x3db504f3, v140
	v_mul_f32_e32 v141, 0x3db504f3, v141
	v_mul_f32_e32 v142, 0x3db504f3, v142
	v_mul_f32_e32 v143, 0x3db504f3, v143
	v_mul_f32_e32 v144, 0x3db504f3, v144
	v_mul_f32_e32 v145, 0x3db504f3, v145
	v_mul_f32_e32 v146, 0x3db504f3, v146
	v_mul_f32_e32 v147, 0x3db504f3, v147
	v_mul_f32_e32 v148, 0x3db504f3, v148
	v_mul_f32_e32 v149, 0x3db504f3, v149
	v_mul_f32_e32 v150, 0x3db504f3, v150
	v_mul_f32_e32 v151, 0x3db504f3, v151
	v_mul_f32_e32 v152, 0x3db504f3, v152
	v_mul_f32_e32 v153, 0x3db504f3, v153
	v_mul_f32_e32 v154, 0x3db504f3, v154
	v_mul_f32_e32 v155, 0x3db504f3, v155
	v_mul_f32_e32 v156, 0x3db504f3, v156
	v_mul_f32_e32 v157, 0x3db504f3, v157
	v_mul_f32_e32 v158, 0x3db504f3, v158
	v_mul_f32_e32 v159, 0x3db504f3, v159
	v_mul_f32_e32 v160, 0x3db504f3, v160
	v_mul_f32_e32 v161, 0x3db504f3, v161
	v_mul_f32_e32 v162, 0x3db504f3, v162
	v_mul_f32_e32 v163, 0x3db504f3, v163
	v_mul_f32_e32 v164, 0x3db504f3, v164
	v_mul_f32_e32 v165, 0x3db504f3, v165
	v_mul_f32_e32 v166, 0x3db504f3, v166
	v_mul_f32_e32 v167, 0x3db504f3, v167
	v_mul_f32_e32 v172, 0x3db504f3, v172
	v_mul_f32_e32 v173, 0x3db504f3, v173
	v_mul_f32_e32 v174, 0x3db504f3, v82
	v_mul_f32_e32 v175, 0x3db504f3, v83
	v_mul_f32_e32 v176, 0x3db504f3, v176
	v_mul_f32_e32 v177, 0x3db504f3, v177
	s_mov_b64 s[48:49], -1
	s_branch .Lp2q_first
.Lp2q_first:
	v_lshl_add_u64 v[82:83], s[50:51], 1, v[6:7]
	s_mov_b64 s[50:51], -1
	s_and_b64 vcc, exec, s[48:49]
	s_barrier
	s_waitcnt vmcnt(7)
	ds_write_b128 v97, v[186:189]
	s_waitcnt vmcnt(6)
	ds_write_b128 v97, v[190:193] offset:8192
	s_waitcnt vmcnt(5)
	ds_write_b128 v97, v[194:197] offset:16384
	s_waitcnt vmcnt(4)
	ds_write_b128 v97, v[198:201] offset:24576
	s_waitcnt vmcnt(3)
	ds_write_b128 v97, v[202:205] offset:32768
	s_waitcnt vmcnt(2)
	ds_write_b128 v97, v[206:209] offset:40960
	s_waitcnt vmcnt(1)
	ds_write_b128 v97, v[210:213] offset:49152
	s_waitcnt vmcnt(0)
	ds_write_b128 v97, v[214:217] offset:57344
	s_waitcnt lgkmcnt(0)
	s_barrier
	s_cbranch_vccnz .LBB0_273
	s_branch .Lp2q_fall

.Lp2q_fall:
	ds_read_u16 v178, v98
	ds_read_u16 v179, v99 offset:256
	ds_read_u16 v180, v100 offset:512
	ds_read_u16 v181, v101 offset:768
	ds_read_u16 v182, v102 offset:1024
	ds_read_u16 v183, v103 offset:1280
	ds_read_u16 v184, v104 offset:1536
	ds_read_u16 v185, v105 offset:1792
	s_waitcnt lgkmcnt(6)
	v_lshlrev_b32_e32 v179, 16, v179
	v_lshlrev_b32_e32 v178, 16, v178
	v_pk_mul_f32 v[178:179], v[8:9], v[178:179]
	s_waitcnt lgkmcnt(4)
	v_lshlrev_b32_e32 v181, 16, v181
	v_cvt_pk_bf16_f32 v186, v178, s0
	v_lshlrev_b32_e32 v180, 16, v180
	ds_write_b16 v98, v186
	v_cvt_pk_bf16_f32 v186, v179, s0
	v_pk_mul_f32 v[180:181], v[10:11], v[180:181]
	ds_write_b16 v99, v186 offset:256
	v_cvt_pk_bf16_f32 v186, v180, s0
	s_waitcnt lgkmcnt(4)
	v_lshlrev_b32_e32 v183, 16, v183
	v_lshlrev_b32_e32 v182, 16, v182
	ds_write_b16 v100, v186 offset:512
	v_cvt_pk_bf16_f32 v186, v181, s0
	v_pk_mul_f32 v[182:183], v[12:13], v[182:183]
	ds_write_b16 v101, v186 offset:768
	v_cvt_pk_bf16_f32 v186, v182, s0
	s_waitcnt lgkmcnt(4)
	v_lshlrev_b32_e32 v185, 16, v185
	v_lshlrev_b32_e32 v184, 16, v184
	ds_write_b16 v102, v186 offset:1024
	v_cvt_pk_bf16_f32 v186, v183, s0
	v_pk_mul_f32 v[184:185], v[14:15], v[184:185]
	ds_write_b16 v103, v186 offset:1280
	v_cvt_pk_bf16_f32 v186, v184, s0
	ds_write_b16 v104, v186 offset:1536
	v_cvt_pk_bf16_f32 v186, v185, s0
	v_cvt_pk_bf16_f32 v178, v178, v179
	v_cvt_pk_bf16_f32 v179, v180, v181
	v_cvt_pk_bf16_f32 v180, v182, v183
	v_cvt_pk_bf16_f32 v181, v184, v185
	ds_write_b16 v105, v186 offset:1792
	ds_write_b128 v89, v[178:181]
	ds_read_u16 v178, v106 offset:2048
	ds_read_u16 v179, v107 offset:2304
	ds_read_u16 v180, v108 offset:2560
	ds_read_u16 v181, v109 offset:2816
	ds_read_u16 v182, v110 offset:3072
	ds_read_u16 v183, v111 offset:3328
	ds_read_u16 v184, v112 offset:3584
	ds_read_u16 v185, v113 offset:3840
	s_waitcnt lgkmcnt(6)
	v_lshlrev_b32_e32 v179, 16, v179
	v_lshlrev_b32_e32 v178, 16, v178
	v_pk_mul_f32 v[178:179], v[16:17], v[178:179]
	s_waitcnt lgkmcnt(4)
	v_lshlrev_b32_e32 v181, 16, v181
	v_cvt_pk_bf16_f32 v186, v178, s0
	v_lshlrev_b32_e32 v180, 16, v180
	ds_write_b16 v106, v186 offset:2048
	v_cvt_pk_bf16_f32 v186, v179, s0
	v_pk_mul_f32 v[180:181], v[18:19], v[180:181]
	ds_write_b16 v107, v186 offset:2304
	v_cvt_pk_bf16_f32 v186, v180, s0
	s_waitcnt lgkmcnt(4)
	v_lshlrev_b32_e32 v183, 16, v183
	v_lshlrev_b32_e32 v182, 16, v182
	ds_write_b16 v108, v186 offset:2560
	v_cvt_pk_bf16_f32 v186, v181, s0
	v_pk_mul_f32 v[182:183], v[20:21], v[182:183]
	ds_write_b16 v109, v186 offset:2816
	v_cvt_pk_bf16_f32 v186, v182, s0
	s_waitcnt lgkmcnt(4)
	v_lshlrev_b32_e32 v185, 16, v185
	v_lshlrev_b32_e32 v184, 16, v184
	ds_write_b16 v110, v186 offset:3072
	v_cvt_pk_bf16_f32 v186, v183, s0
	v_pk_mul_f32 v[184:185], v[22:23], v[184:185]
	ds_write_b16 v111, v186 offset:3328
	v_cvt_pk_bf16_f32 v186, v184, s0
	ds_write_b16 v112, v186 offset:3584
	v_cvt_pk_bf16_f32 v186, v185, s0
	v_cvt_pk_bf16_f32 v178, v178, v179
	v_cvt_pk_bf16_f32 v179, v180, v181
	v_cvt_pk_bf16_f32 v180, v182, v183
	v_cvt_pk_bf16_f32 v181, v184, v185
	ds_write_b16 v113, v186 offset:3840
	ds_write_b128 v90, v[178:181]
	ds_read_u16 v178, v98 offset:4096
	ds_read_u16 v179, v99 offset:4352
	ds_read_u16 v180, v100 offset:4608
	ds_read_u16 v181, v101 offset:4864
	ds_read_u16 v182, v102 offset:5120
	ds_read_u16 v183, v103 offset:5376
	ds_read_u16 v184, v104 offset:5632
	ds_read_u16 v185, v105 offset:5888
	s_waitcnt lgkmcnt(6)
	v_lshlrev_b32_e32 v179, 16, v179
	v_lshlrev_b32_e32 v178, 16, v178
	v_pk_mul_f32 v[178:179], v[24:25], v[178:179]
	s_waitcnt lgkmcnt(4)
	v_lshlrev_b32_e32 v181, 16, v181
	v_cvt_pk_bf16_f32 v186, v178, s0
	v_lshlrev_b32_e32 v180, 16, v180
	ds_write_b16 v98, v186 offset:4096
	v_cvt_pk_bf16_f32 v186, v179, s0
	v_pk_mul_f32 v[180:181], v[26:27], v[180:181]
	ds_write_b16 v99, v186 offset:4352
	v_cvt_pk_bf16_f32 v186, v180, s0
	s_waitcnt lgkmcnt(4)
	v_lshlrev_b32_e32 v183, 16, v183
	v_lshlrev_b32_e32 v182, 16, v182
	ds_write_b16 v100, v186 offset:4608
	v_cvt_pk_bf16_f32 v186, v181, s0
	v_pk_mul_f32 v[182:183], v[28:29], v[182:183]
	ds_write_b16 v101, v186 offset:4864
	v_cvt_pk_bf16_f32 v186, v182, s0
	s_waitcnt lgkmcnt(4)
	v_lshlrev_b32_e32 v185, 16, v185
	v_lshlrev_b32_e32 v184, 16, v184
	ds_write_b16 v102, v186 offset:5120
	v_cvt_pk_bf16_f32 v186, v183, s0
	v_pk_mul_f32 v[184:185], v[30:31], v[184:185]
	ds_write_b16 v103, v186 offset:5376
	v_cvt_pk_bf16_f32 v186, v184, s0
	ds_write_b16 v104, v186 offset:5632
	v_cvt_pk_bf16_f32 v186, v185, s0
	v_cvt_pk_bf16_f32 v178, v178, v179
	v_cvt_pk_bf16_f32 v179, v180, v181
	v_cvt_pk_bf16_f32 v180, v182, v183
	v_cvt_pk_bf16_f32 v181, v184, v185
	ds_write_b16 v105, v186 offset:5888
	ds_write_b128 v91, v[178:181]
	ds_read_u16 v178, v106 offset:6144
	ds_read_u16 v179, v107 offset:6400
	ds_read_u16 v180, v108 offset:6656
	ds_read_u16 v181, v109 offset:6912
	ds_read_u16 v182, v110 offset:7168
	ds_read_u16 v183, v111 offset:7424
	ds_read_u16 v184, v112 offset:7680
	ds_read_u16 v185, v113 offset:7936
	s_waitcnt lgkmcnt(6)
	v_lshlrev_b32_e32 v179, 16, v179
	v_lshlrev_b32_e32 v178, 16, v178
	v_pk_mul_f32 v[178:179], v[32:33], v[178:179]
	s_waitcnt lgkmcnt(4)
	v_lshlrev_b32_e32 v181, 16, v181
	v_cvt_pk_bf16_f32 v186, v178, s0
	v_lshlrev_b32_e32 v180, 16, v180
	ds_write_b16 v106, v186 offset:6144
	v_cvt_pk_bf16_f32 v186, v179, s0
	v_pk_mul_f32 v[180:181], v[34:35], v[180:181]
	ds_write_b16 v107, v186 offset:6400
	v_cvt_pk_bf16_f32 v186, v180, s0
	s_waitcnt lgkmcnt(4)
	v_lshlrev_b32_e32 v183, 16, v183
	v_lshlrev_b32_e32 v182, 16, v182
	ds_write_b16 v108, v186 offset:6656
	v_cvt_pk_bf16_f32 v186, v181, s0
	v_pk_mul_f32 v[182:183], v[36:37], v[182:183]
	ds_write_b16 v109, v186 offset:6912
	v_cvt_pk_bf16_f32 v186, v182, s0
	s_waitcnt lgkmcnt(4)
	v_lshlrev_b32_e32 v185, 16, v185
	v_lshlrev_b32_e32 v184, 16, v184
	ds_write_b16 v110, v186 offset:7168
	v_cvt_pk_bf16_f32 v186, v183, s0
	v_pk_mul_f32 v[184:185], v[38:39], v[184:185]
	ds_write_b16 v111, v186 offset:7424
	v_cvt_pk_bf16_f32 v186, v184, s0
	ds_write_b16 v112, v186 offset:7680
	v_cvt_pk_bf16_f32 v186, v185, s0
	v_cvt_pk_bf16_f32 v178, v178, v179
	v_cvt_pk_bf16_f32 v179, v180, v181
	v_cvt_pk_bf16_f32 v180, v182, v183
	v_cvt_pk_bf16_f32 v181, v184, v185
	ds_write_b16 v113, v186 offset:7936
	ds_write_b128 v92, v[178:181]
	ds_read_u16 v178, v98 offset:8192
	ds_read_u16 v179, v99 offset:8448
	ds_read_u16 v180, v100 offset:8704
	ds_read_u16 v181, v101 offset:8960
	ds_read_u16 v182, v102 offset:9216
	ds_read_u16 v183, v103 offset:9472
	ds_read_u16 v184, v104 offset:9728
	ds_read_u16 v185, v105 offset:9984
	s_waitcnt lgkmcnt(6)
	v_lshlrev_b32_e32 v179, 16, v179
	v_lshlrev_b32_e32 v178, 16, v178
	v_pk_mul_f32 v[178:179], v[40:41], v[178:179]
	s_waitcnt lgkmcnt(4)
	v_lshlrev_b32_e32 v181, 16, v181
	v_cvt_pk_bf16_f32 v186, v178, s0
	v_lshlrev_b32_e32 v180, 16, v180
	ds_write_b16 v98, v186 offset:8192
	v_cvt_pk_bf16_f32 v186, v179, s0
	v_pk_mul_f32 v[180:181], v[42:43], v[180:181]
	ds_write_b16 v99, v186 offset:8448
	v_cvt_pk_bf16_f32 v186, v180, s0
	s_waitcnt lgkmcnt(4)
	v_lshlrev_b32_e32 v183, 16, v183
	v_lshlrev_b32_e32 v182, 16, v182
	ds_write_b16 v100, v186 offset:8704
	v_cvt_pk_bf16_f32 v186, v181, s0
	v_pk_mul_f32 v[182:183], v[44:45], v[182:183]
	ds_write_b16 v101, v186 offset:8960
	v_cvt_pk_bf16_f32 v186, v182, s0
	s_waitcnt lgkmcnt(4)
	v_lshlrev_b32_e32 v185, 16, v185
	v_lshlrev_b32_e32 v184, 16, v184
	ds_write_b16 v102, v186 offset:9216
	v_cvt_pk_bf16_f32 v186, v183, s0
	v_pk_mul_f32 v[184:185], v[46:47], v[184:185]
	ds_write_b16 v103, v186 offset:9472
	v_cvt_pk_bf16_f32 v186, v184, s0
	ds_write_b16 v104, v186 offset:9728
	v_cvt_pk_bf16_f32 v186, v185, s0
	v_cvt_pk_bf16_f32 v178, v178, v179
	v_cvt_pk_bf16_f32 v179, v180, v181
	v_cvt_pk_bf16_f32 v180, v182, v183
	v_cvt_pk_bf16_f32 v181, v184, v185
	ds_write_b16 v105, v186 offset:9984
	ds_write_b128 v93, v[178:181]
	ds_read_u16 v178, v106 offset:10240
	ds_read_u16 v179, v107 offset:10496
	ds_read_u16 v180, v108 offset:10752
	ds_read_u16 v181, v109 offset:11008
	ds_read_u16 v182, v110 offset:11264
	ds_read_u16 v183, v111 offset:11520
	ds_read_u16 v184, v112 offset:11776
	ds_read_u16 v185, v113 offset:12032
	s_waitcnt lgkmcnt(6)
	v_lshlrev_b32_e32 v179, 16, v179
	v_lshlrev_b32_e32 v178, 16, v178
	v_pk_mul_f32 v[178:179], v[48:49], v[178:179]
	s_waitcnt lgkmcnt(4)
	v_lshlrev_b32_e32 v181, 16, v181
	v_cvt_pk_bf16_f32 v186, v178, s0
	v_lshlrev_b32_e32 v180, 16, v180
	ds_write_b16 v106, v186 offset:10240
	v_cvt_pk_bf16_f32 v186, v179, s0
	v_pk_mul_f32 v[180:181], v[50:51], v[180:181]
	ds_write_b16 v107, v186 offset:10496
	v_cvt_pk_bf16_f32 v186, v180, s0
	s_waitcnt lgkmcnt(4)
	v_lshlrev_b32_e32 v183, 16, v183
	v_lshlrev_b32_e32 v182, 16, v182
	ds_write_b16 v108, v186 offset:10752
	v_cvt_pk_bf16_f32 v186, v181, s0
	v_pk_mul_f32 v[182:183], v[52:53], v[182:183]
	ds_write_b16 v109, v186 offset:11008
	v_cvt_pk_bf16_f32 v186, v182, s0
	s_waitcnt lgkmcnt(4)
	v_lshlrev_b32_e32 v185, 16, v185
	v_lshlrev_b32_e32 v184, 16, v184
	ds_write_b16 v110, v186 offset:11264
	v_cvt_pk_bf16_f32 v186, v183, s0
	v_pk_mul_f32 v[184:185], v[54:55], v[184:185]
	ds_write_b16 v111, v186 offset:11520
	v_cvt_pk_bf16_f32 v186, v184, s0
	ds_write_b16 v112, v186 offset:11776
	v_cvt_pk_bf16_f32 v186, v185, s0
	v_cvt_pk_bf16_f32 v178, v178, v179
	v_cvt_pk_bf16_f32 v179, v180, v181
	v_cvt_pk_bf16_f32 v180, v182, v183
	v_cvt_pk_bf16_f32 v181, v184, v185
	ds_write_b16 v113, v186 offset:12032
	ds_write_b128 v94, v[178:181]
	ds_read_u16 v178, v98 offset:12288
	ds_read_u16 v179, v99 offset:12544
	ds_read_u16 v180, v100 offset:12800
	ds_read_u16 v181, v101 offset:13056
	ds_read_u16 v182, v102 offset:13312
	ds_read_u16 v183, v103 offset:13568
	ds_read_u16 v184, v104 offset:13824
	ds_read_u16 v185, v105 offset:14080
	s_waitcnt lgkmcnt(6)
	v_lshlrev_b32_e32 v179, 16, v179
	v_lshlrev_b32_e32 v178, 16, v178
	v_pk_mul_f32 v[178:179], v[56:57], v[178:179]
	s_waitcnt lgkmcnt(4)
	v_lshlrev_b32_e32 v181, 16, v181
	v_cvt_pk_bf16_f32 v186, v178, s0
	v_lshlrev_b32_e32 v180, 16, v180
	ds_write_b16 v98, v186 offset:12288
	v_cvt_pk_bf16_f32 v186, v179, s0
	v_pk_mul_f32 v[180:181], v[58:59], v[180:181]
	ds_write_b16 v99, v186 offset:12544
	v_cvt_pk_bf16_f32 v186, v180, s0
	s_waitcnt lgkmcnt(4)
	v_lshlrev_b32_e32 v183, 16, v183
	v_lshlrev_b32_e32 v182, 16, v182
	ds_write_b16 v100, v186 offset:12800
	v_cvt_pk_bf16_f32 v186, v181, s0
	v_pk_mul_f32 v[182:183], v[60:61], v[182:183]
	ds_write_b16 v101, v186 offset:13056
	v_cvt_pk_bf16_f32 v186, v182, s0
	s_waitcnt lgkmcnt(4)
	v_lshlrev_b32_e32 v185, 16, v185
	v_lshlrev_b32_e32 v184, 16, v184
	ds_write_b16 v102, v186 offset:13312
	v_cvt_pk_bf16_f32 v186, v183, s0
	v_pk_mul_f32 v[184:185], v[72:73], v[184:185]
	ds_write_b16 v103, v186 offset:13568
	v_cvt_pk_bf16_f32 v186, v184, s0
	ds_write_b16 v104, v186 offset:13824
	v_cvt_pk_bf16_f32 v186, v185, s0
	v_cvt_pk_bf16_f32 v178, v178, v179
	v_cvt_pk_bf16_f32 v179, v180, v181
	v_cvt_pk_bf16_f32 v180, v182, v183
	v_cvt_pk_bf16_f32 v181, v184, v185
	ds_write_b16 v105, v186 offset:14080
	ds_write_b128 v95, v[178:181]
	ds_read_u16 v178, v106 offset:14336
	ds_read_u16 v179, v107 offset:14592
	ds_read_u16 v180, v108 offset:14848
	ds_read_u16 v181, v109 offset:15104
	ds_read_u16 v182, v110 offset:15360
	ds_read_u16 v183, v111 offset:15616
	ds_read_u16 v184, v112 offset:15872
	ds_read_u16 v185, v113 offset:16128
	s_waitcnt lgkmcnt(6)
	v_lshlrev_b32_e32 v179, 16, v179
	v_lshlrev_b32_e32 v178, 16, v178
	v_pk_mul_f32 v[178:179], v[74:75], v[178:179]
	s_waitcnt lgkmcnt(4)
	v_lshlrev_b32_e32 v181, 16, v181
	v_cvt_pk_bf16_f32 v186, v178, s0
	v_lshlrev_b32_e32 v180, 16, v180
	ds_write_b16 v106, v186 offset:14336
	v_cvt_pk_bf16_f32 v186, v179, s0
	v_pk_mul_f32 v[180:181], v[76:77], v[180:181]
	ds_write_b16 v107, v186 offset:14592
	v_cvt_pk_bf16_f32 v186, v180, s0
	s_waitcnt lgkmcnt(4)
	v_lshlrev_b32_e32 v183, 16, v183
	v_lshlrev_b32_e32 v182, 16, v182
	ds_write_b16 v108, v186 offset:14848
	v_cvt_pk_bf16_f32 v186, v181, s0
	v_pk_mul_f32 v[182:183], v[78:79], v[182:183]
	ds_write_b16 v109, v186 offset:15104
	v_cvt_pk_bf16_f32 v186, v182, s0
	s_waitcnt lgkmcnt(4)
	v_lshlrev_b32_e32 v185, 16, v185
	v_lshlrev_b32_e32 v184, 16, v184
	ds_write_b16 v110, v186 offset:15360
	v_cvt_pk_bf16_f32 v186, v183, s0
	v_pk_mul_f32 v[184:185], v[80:81], v[184:185]
	ds_write_b16 v111, v186 offset:15616
	v_cvt_pk_bf16_f32 v186, v184, s0
	ds_write_b16 v112, v186 offset:15872
	v_cvt_pk_bf16_f32 v186, v185, s0
	v_cvt_pk_bf16_f32 v178, v178, v179
	v_cvt_pk_bf16_f32 v179, v180, v181
	v_cvt_pk_bf16_f32 v180, v182, v183
	v_cvt_pk_bf16_f32 v181, v184, v185
	s_mov_b64 s[50:51], 0
	ds_write_b16 v113, v186 offset:16128
	ds_write_b128 v96, v[178:181]
